# SwiGLU epilogue: per-row norm slots prefetched one row-group ahead into free registers, output store deferred behind the next prefetch (counted vmcnt)
# speedup vs baseline: 1.0048x; 1.0048x over previous
.LBB0_165:
	v_ashrrev_i32_e32 v153, 31, v152
	v_lshlrev_b64 v[154:155], 6, v[152:153]
	v_lshl_add_u64 v[170:171], s[74:75], 0, v[154:155]
	s_waitcnt lgkmcnt(0)
	s_nop 0
	v_mov_b32_e32 v174, v124
	v_mov_b32_e32 v175, v116
	v_mov_b32_e32 v116, v125
	v_mov_b32_e32 v124, v126
	v_mov_b32_e32 v125, v118
	v_mov_b32_e32 v118, v127
	v_mov_b32_e32 v126, v120
	v_mov_b32_e32 v127, v112
	v_mov_b32_e32 v112, v121
	v_mov_b32_e32 v176, v122
	v_mov_b32_e32 v177, v114
	v_mov_b32_e32 v114, v123
	s_lshl_b32 s24, s24, 7
	v_mov_b64_e32 v[120:121], s[72:73]
	s_ashr_i32 s25, s24, 31
	v_mad_i64_i32 v[122:123], s[26:27], v152, s51, v[120:121]
	s_lshl_b64 s[24:25], s[24:25], 1
	v_lshl_add_u64 v[122:123], v[122:123], 0, s[24:25]
	v_lshl_add_u64 v[122:123], v[122:123], 0, s[6:7]
	v_mov_b32_e32 v212, v152
	v_ashrrev_i32_e32 v213, 31, v212
	v_lshlrev_b64 v[212:213], 6, v[212:213]
	v_lshl_add_u64 v[212:213], s[74:75], 0, v[212:213]
	global_load_dwordx4 v[180:183], v[212:213], off
	global_load_dwordx4 v[184:187], v[212:213], off offset:16
	global_load_dwordx4 v[188:191], v[212:213], off offset:32
	global_load_dwordx4 v[192:195], v[212:213], off offset:48
	v_or_b32_e32 v212, 16, v152
	v_ashrrev_i32_e32 v213, 31, v212
	v_lshlrev_b64 v[212:213], 6, v[212:213]
	v_lshl_add_u64 v[212:213], s[74:75], 0, v[212:213]
	global_load_dwordx4 v[196:199], v[212:213], off
	global_load_dwordx4 v[200:203], v[212:213], off offset:16
	global_load_dwordx4 v[204:207], v[212:213], off offset:32
	global_load_dwordx4 v[208:211], v[212:213], off offset:48
	s_waitcnt vmcnt(6)
	v_pk_add_f32 v[180:181], v[180:181], v[182:183]
	v_pk_add_f32 v[184:185], v[184:185], v[186:187]
	s_waitcnt vmcnt(4)
	v_pk_add_f32 v[188:189], v[188:189], v[190:191]
	v_pk_add_f32 v[192:193], v[192:193], v[194:195]
	v_pk_add_f32 v[180:181], v[180:181], v[184:185]
	v_pk_add_f32 v[188:189], v[188:189], v[192:193]
	v_mul_f32_e32 v116, v116, v117
	v_mul_f32_e32 v124, v124, v125
	v_mul_f32_e32 v118, v118, v119
	v_mul_f32_e32 v126, v126, v127
	v_pk_add_f32 v[180:181], v[180:181], v[188:189]
	v_mul_f32_e32 v174, v174, v175
	v_mul_f32_e32 v112, v112, v113
	v_mul_f32_e32 v176, v176, v177
	v_mul_f32_e32 v114, v114, v115
	v_add_f32_e32 v180, v180, v181
	v_fmamk_f32 v180, v180, 0x3a800000, v160
	v_rsq_f32_e32 v181, v180
	s_nop 0
	v_mul_f32_e32 v181, 0xbfb8aa3b, v181
	v_mul_f32_e32 v117, v181, v117
	v_mul_f32_e32 v125, v181, v125
	v_mul_f32_e32 v119, v181, v119
	v_mul_f32_e32 v127, v181, v127
	v_mul_f32_e32 v175, v181, v175
	v_mul_f32_e32 v113, v181, v113
	v_mul_f32_e32 v177, v181, v177
	v_mul_f32_e32 v115, v181, v115
	v_exp_f32_e32 v117, v117
	v_exp_f32_e32 v125, v125
	v_exp_f32_e32 v119, v119
	v_exp_f32_e32 v127, v127
	v_exp_f32_e32 v175, v175
	v_exp_f32_e32 v113, v113
	v_exp_f32_e32 v177, v177
	v_exp_f32_e32 v115, v115
	v_fma_f32 v117, v117, v180, v180
	v_fma_f32 v125, v125, v180, v180
	v_fma_f32 v119, v119, v180, v180
	v_fma_f32 v127, v127, v180, v180
	v_fma_f32 v175, v175, v180, v180
	v_fma_f32 v113, v113, v180, v180
	v_fma_f32 v177, v177, v180, v180
	v_fma_f32 v115, v115, v180, v180
	v_rcp_f32_e32 v117, v117
	v_rcp_f32_e32 v125, v125
	v_rcp_f32_e32 v119, v119
	v_rcp_f32_e32 v127, v127
	v_rcp_f32_e32 v175, v175
	v_rcp_f32_e32 v113, v113
	v_rcp_f32_e32 v177, v177
	v_rcp_f32_e32 v115, v115
	v_mul_f32_e32 v116, v116, v117
	v_mul_f32_e32 v124, v124, v125
	v_mul_f32_e32 v118, v118, v119
	v_mul_f32_e32 v126, v126, v127
	v_mul_f32_e32 v174, v174, v175
	v_mul_f32_e32 v112, v112, v113
	v_mul_f32_e32 v176, v176, v177
	v_mul_f32_e32 v114, v114, v115
	v_cvt_pk_bf16_f32 v216, v174, v116
	v_cvt_pk_bf16_f32 v217, v124, v118
	v_cvt_pk_bf16_f32 v218, v126, v112
	v_cvt_pk_bf16_f32 v219, v176, v114
	v_or_b32_e32 v126, 16, v152
	v_lshl_add_u64 v[116:117], v[122:123], 0, v[136:137]
	v_ashrrev_i32_e32 v127, 31, v126
	v_mov_b32_e32 v224, v116
	v_mov_b32_e32 v225, v117
	v_mov_b32_e32 v162, v108
	v_mov_b32_e32 v163, v100
	v_lshlrev_b64 v[112:113], 6, v[126:127]
	v_lshl_add_u64 v[154:155], s[74:75], 0, v[112:113]
	s_nop 0
	v_mov_b32_e32 v100, v109
	v_mov_b32_e32 v108, v110
	v_mov_b32_e32 v109, v102
	v_mov_b32_e32 v102, v111
	v_mov_b32_e32 v110, v104
	v_mov_b32_e32 v111, v96
	v_mov_b32_e32 v96, v105
	v_mov_b32_e32 v104, v106
	v_mov_b32_e32 v105, v98
	v_mov_b32_e32 v98, v107
	v_or_b32_e32 v212, 32, v152
	v_ashrrev_i32_e32 v213, 31, v212
	v_lshlrev_b64 v[212:213], 6, v[212:213]
	v_lshl_add_u64 v[212:213], s[74:75], 0, v[212:213]
	global_load_dwordx4 v[180:183], v[212:213], off
	global_load_dwordx4 v[184:187], v[212:213], off offset:16
	global_load_dwordx4 v[188:191], v[212:213], off offset:32
	global_load_dwordx4 v[192:195], v[212:213], off offset:48
	global_store_dwordx4 v[224:225], v[216:219], off
	s_waitcnt vmcnt(7)
	v_pk_add_f32 v[196:197], v[196:197], v[198:199]
	v_pk_add_f32 v[200:201], v[200:201], v[202:203]
	s_waitcnt vmcnt(5)
	v_pk_add_f32 v[204:205], v[204:205], v[206:207]
	v_pk_add_f32 v[208:209], v[208:209], v[210:211]
	v_pk_add_f32 v[196:197], v[196:197], v[200:201]
	v_pk_add_f32 v[204:205], v[204:205], v[208:209]
	v_mul_f32_e32 v100, v100, v101
	v_mul_f32_e32 v108, v108, v109
	v_mul_f32_e32 v162, v162, v163
	v_mul_f32_e32 v102, v102, v103
	v_pk_add_f32 v[196:197], v[196:197], v[204:205]
	v_mul_f32_e32 v110, v110, v111
	v_mul_f32_e32 v96, v96, v97
	v_mul_f32_e32 v104, v104, v105
	v_mul_f32_e32 v98, v98, v99
	v_add_f32_e32 v196, v196, v197
	v_fmamk_f32 v196, v196, 0x3a800000, v160
	v_rsq_f32_e32 v197, v196
	s_nop 0
	v_mul_f32_e32 v197, 0xbfb8aa3b, v197
	v_mul_f32_e32 v101, v197, v101
	v_mul_f32_e32 v109, v197, v109
	v_mul_f32_e32 v163, v197, v163
	v_mul_f32_e32 v103, v197, v103
	v_mul_f32_e32 v111, v197, v111
	v_mul_f32_e32 v97, v197, v97
	v_mul_f32_e32 v105, v197, v105
	v_mul_f32_e32 v99, v197, v99
	v_exp_f32_e32 v101, v101
	v_exp_f32_e32 v109, v109
	v_exp_f32_e32 v163, v163
	v_exp_f32_e32 v103, v103
	v_exp_f32_e32 v111, v111
	v_exp_f32_e32 v97, v97
	v_exp_f32_e32 v105, v105
	v_exp_f32_e32 v99, v99
	v_fma_f32 v101, v101, v196, v196
	v_fma_f32 v109, v109, v196, v196
	v_fma_f32 v163, v163, v196, v196
	v_fma_f32 v103, v103, v196, v196
	v_fma_f32 v111, v111, v196, v196
	v_fma_f32 v97, v97, v196, v196
	v_fma_f32 v105, v105, v196, v196
	v_fma_f32 v99, v99, v196, v196
	v_rcp_f32_e32 v101, v101
	v_rcp_f32_e32 v109, v109
	v_rcp_f32_e32 v163, v163
	v_rcp_f32_e32 v103, v103
	v_rcp_f32_e32 v111, v111
	v_rcp_f32_e32 v97, v97
	v_rcp_f32_e32 v105, v105
	v_rcp_f32_e32 v99, v99
	v_mul_f32_e32 v100, v100, v101
	v_mul_f32_e32 v108, v108, v109
	v_mul_f32_e32 v162, v162, v163
	v_mul_f32_e32 v102, v102, v103
	v_mul_f32_e32 v110, v110, v111
	v_mul_f32_e32 v96, v96, v97
	v_mul_f32_e32 v104, v104, v105
	v_mul_f32_e32 v98, v98, v99
	v_cvt_pk_bf16_f32 v220, v162, v100
	v_cvt_pk_bf16_f32 v221, v108, v102
	v_cvt_pk_bf16_f32 v222, v110, v96
	v_cvt_pk_bf16_f32 v223, v104, v98
	v_mad_i64_i32 v[112:113], s[26:27], v126, s51, v[120:121]
	v_lshl_add_u64 v[112:113], v[112:113], 0, s[24:25]
	v_lshl_add_u64 v[100:101], v[112:113], 0, s[6:7]
	v_or_b32_e32 v112, 32, v152
	v_lshl_add_u64 v[100:101], v[100:101], 0, v[136:137]
	v_ashrrev_i32_e32 v113, 31, v112
	v_mov_b32_e32 v226, v100
	v_mov_b32_e32 v227, v101
	v_mov_b32_e32 v114, v92
	v_mov_b32_e32 v92, v94
	v_lshlrev_b64 v[96:97], 6, v[112:113]
	v_lshl_add_u64 v[108:109], s[74:75], 0, v[96:97]
	s_nop 0
	v_mov_b32_e32 v94, v80
	v_mov_b32_e32 v80, v82
	v_mov_b32_e32 v115, v88
	v_mov_b32_e32 v88, v93
	v_mov_b32_e32 v93, v90
	v_mov_b32_e32 v90, v95
	v_mov_b32_e32 v95, v84
	v_mov_b32_e32 v84, v81
	v_mov_b32_e32 v81, v86
	v_mov_b32_e32 v86, v83
	v_or_b32_e32 v212, 48, v152
	v_ashrrev_i32_e32 v213, 31, v212
	v_lshlrev_b64 v[212:213], 6, v[212:213]
	v_lshl_add_u64 v[212:213], s[74:75], 0, v[212:213]
	global_load_dwordx4 v[196:199], v[212:213], off
	global_load_dwordx4 v[200:203], v[212:213], off offset:16
	global_load_dwordx4 v[204:207], v[212:213], off offset:32
	global_load_dwordx4 v[208:211], v[212:213], off offset:48
	global_store_dwordx4 v[226:227], v[220:223], off
	s_waitcnt vmcnt(7)
	v_pk_add_f32 v[180:181], v[180:181], v[182:183]
	v_pk_add_f32 v[184:185], v[184:185], v[186:187]
	s_waitcnt vmcnt(5)
	v_pk_add_f32 v[188:189], v[188:189], v[190:191]
	v_pk_add_f32 v[192:193], v[192:193], v[194:195]
	v_pk_add_f32 v[180:181], v[180:181], v[184:185]
	v_pk_add_f32 v[188:189], v[188:189], v[192:193]
	v_mul_f32_e32 v114, v114, v115
	v_mul_f32_e32 v88, v88, v89
	v_mul_f32_e32 v92, v92, v93
	v_mul_f32_e32 v90, v90, v91
	v_pk_add_f32 v[180:181], v[180:181], v[188:189]
	v_mul_f32_e32 v94, v94, v95
	v_mul_f32_e32 v84, v84, v85
	v_mul_f32_e32 v80, v80, v81
	v_mul_f32_e32 v86, v86, v87
	v_add_f32_e32 v180, v180, v181
	v_fmamk_f32 v180, v180, 0x3a800000, v160
	v_rsq_f32_e32 v181, v180
	s_nop 0
	v_mul_f32_e32 v181, 0xbfb8aa3b, v181
	v_mul_f32_e32 v115, v181, v115
	v_mul_f32_e32 v89, v181, v89
	v_mul_f32_e32 v93, v181, v93
	v_mul_f32_e32 v91, v181, v91
	v_mul_f32_e32 v95, v181, v95
	v_mul_f32_e32 v85, v181, v85
	v_mul_f32_e32 v81, v181, v81
	v_mul_f32_e32 v87, v181, v87
	v_exp_f32_e32 v115, v115
	v_exp_f32_e32 v89, v89
	v_exp_f32_e32 v93, v93
	v_exp_f32_e32 v91, v91
	v_exp_f32_e32 v95, v95
	v_exp_f32_e32 v85, v85
	v_exp_f32_e32 v81, v81
	v_exp_f32_e32 v87, v87
	v_fma_f32 v115, v115, v180, v180
	v_fma_f32 v89, v89, v180, v180
	v_fma_f32 v93, v93, v180, v180
	v_fma_f32 v91, v91, v180, v180
	v_fma_f32 v95, v95, v180, v180
	v_fma_f32 v85, v85, v180, v180
	v_fma_f32 v81, v81, v180, v180
	v_fma_f32 v87, v87, v180, v180
	v_rcp_f32_e32 v115, v115
	v_rcp_f32_e32 v89, v89
	v_rcp_f32_e32 v93, v93
	v_rcp_f32_e32 v91, v91
	v_rcp_f32_e32 v95, v95
	v_rcp_f32_e32 v85, v85
	v_rcp_f32_e32 v81, v81
	v_rcp_f32_e32 v87, v87
	v_mul_f32_e32 v114, v114, v115
	v_mul_f32_e32 v88, v88, v89
	v_mul_f32_e32 v92, v92, v93
	v_mul_f32_e32 v90, v90, v91
	v_mul_f32_e32 v94, v94, v95
	v_mul_f32_e32 v84, v84, v85
	v_mul_f32_e32 v80, v80, v81
	v_mul_f32_e32 v86, v86, v87
	v_cvt_pk_bf16_f32 v216, v114, v88
	v_cvt_pk_bf16_f32 v217, v92, v90
	v_cvt_pk_bf16_f32 v218, v94, v84
	v_cvt_pk_bf16_f32 v219, v80, v86
	v_mad_i64_i32 v[96:97], s[26:27], v112, s51, v[120:121]
	v_lshl_add_u64 v[84:85], v[96:97], 0, s[24:25]
	v_lshl_add_u64 v[84:85], v[84:85], 0, s[6:7]
	v_or_b32_e32 v96, 48, v152
	v_lshl_add_u64 v[84:85], v[84:85], 0, v[136:137]
	v_ashrrev_i32_e32 v97, 31, v96
	v_mov_b32_e32 v224, v84
	v_mov_b32_e32 v225, v85
	v_mov_b32_e32 v98, v76
	v_mov_b32_e32 v99, v72
	v_lshlrev_b64 v[80:81], 6, v[96:97]
	v_lshl_add_u64 v[92:93], s[74:75], 0, v[80:81]
	s_nop 0
	v_mov_b32_e32 v72, v77
	v_mov_b32_e32 v76, v78
	v_mov_b32_e32 v77, v74
	v_mov_b32_e32 v74, v79
	v_mov_b32_e32 v78, v64
	v_mov_b32_e32 v79, v68
	v_mov_b32_e32 v68, v65
	v_add_u32_e32 v212, 0x80, v152
	v_ashrrev_i32_e32 v213, 31, v212
	v_lshlrev_b64 v[212:213], 6, v[212:213]
	v_lshl_add_u64 v[212:213], s[74:75], 0, v[212:213]
	global_load_dwordx4 v[180:183], v[212:213], off
	global_load_dwordx4 v[184:187], v[212:213], off offset:16
	global_load_dwordx4 v[188:191], v[212:213], off offset:32
	global_load_dwordx4 v[192:195], v[212:213], off offset:48
	global_store_dwordx4 v[224:225], v[216:219], off
	s_waitcnt vmcnt(7)
	v_pk_add_f32 v[196:197], v[196:197], v[198:199]
	v_pk_add_f32 v[200:201], v[200:201], v[202:203]
	s_waitcnt vmcnt(5)
	v_pk_add_f32 v[204:205], v[204:205], v[206:207]
	v_pk_add_f32 v[208:209], v[208:209], v[210:211]
	v_pk_add_f32 v[196:197], v[196:197], v[200:201]
	v_pk_add_f32 v[204:205], v[204:205], v[208:209]
	v_mul_f32_e32 v98, v98, v99
	v_mul_f32_e32 v72, v72, v73
	v_mul_f32_e32 v76, v76, v77
	v_mul_f32_e32 v68, v68, v69
	v_pk_add_f32 v[196:197], v[196:197], v[204:205]
	v_mul_f32_e32 v66, v66, v70
	v_mul_f32_e32 v74, v74, v75
	v_mul_f32_e32 v78, v78, v79
	v_mul_f32_e32 v67, v67, v71
	v_add_f32_e32 v196, v196, v197
	v_fmamk_f32 v196, v196, 0x3a800000, v160
	v_rsq_f32_e32 v197, v196
	s_nop 0
	v_mul_f32_e32 v197, 0xbfb8aa3b, v197
	v_mul_f32_e32 v99, v197, v99
	v_mul_f32_e32 v73, v197, v73
	v_mul_f32_e32 v77, v197, v77
	v_mul_f32_e32 v69, v197, v69
	v_mul_f32_e32 v70, v197, v70
	v_mul_f32_e32 v75, v197, v75
	v_mul_f32_e32 v79, v197, v79
	v_mul_f32_e32 v71, v197, v71
	v_exp_f32_e32 v99, v99
	v_exp_f32_e32 v73, v73
	v_exp_f32_e32 v77, v77
	v_exp_f32_e32 v69, v69
	v_exp_f32_e32 v70, v70
	v_exp_f32_e32 v75, v75
	v_exp_f32_e32 v79, v79
	v_exp_f32_e32 v71, v71
	v_fma_f32 v99, v99, v196, v196
	v_fma_f32 v73, v73, v196, v196
	v_fma_f32 v77, v77, v196, v196
	v_fma_f32 v69, v69, v196, v196
	v_fma_f32 v70, v70, v196, v196
	v_fma_f32 v75, v75, v196, v196
	v_fma_f32 v79, v79, v196, v196
	v_fma_f32 v71, v71, v196, v196
	v_rcp_f32_e32 v99, v99
	v_rcp_f32_e32 v73, v73
	v_rcp_f32_e32 v77, v77
	v_rcp_f32_e32 v69, v69
	v_rcp_f32_e32 v70, v70
	v_rcp_f32_e32 v75, v75
	v_rcp_f32_e32 v79, v79
	v_rcp_f32_e32 v71, v71
	v_mul_f32_e32 v98, v98, v99
	v_mul_f32_e32 v72, v72, v73
	v_mul_f32_e32 v76, v76, v77
	v_mul_f32_e32 v68, v68, v69
	v_mul_f32_e32 v66, v66, v70
	v_mul_f32_e32 v74, v74, v75
	v_mul_f32_e32 v78, v78, v79
	v_mul_f32_e32 v67, v67, v71
	v_cvt_pk_bf16_f32 v220, v98, v72
	v_cvt_pk_bf16_f32 v221, v76, v74
	v_cvt_pk_bf16_f32 v222, v78, v68
	v_cvt_pk_bf16_f32 v223, v66, v67
	v_mad_i64_i32 v[68:69], s[26:27], v96, s51, v[120:121]
	v_lshl_add_u64 v[68:69], v[68:69], 0, s[24:25]
	v_lshl_add_u64 v[68:69], v[68:69], 0, s[6:7]
	v_add_u32_e32 v80, 0x80, v152
	v_lshl_add_u64 v[68:69], v[68:69], 0, v[136:137]
	v_ashrrev_i32_e32 v81, 31, v80
	v_mov_b32_e32 v226, v68
	v_mov_b32_e32 v227, v69
	v_mov_b32_e32 v82, v60
	v_mov_b32_e32 v83, v56
	v_lshlrev_b64 v[64:65], 6, v[80:81]
	v_lshl_add_u64 v[76:77], s[74:75], 0, v[64:65]
	s_nop 0
	v_mov_b32_e32 v56, v61
	v_mov_b32_e32 v60, v62
	v_mov_b32_e32 v61, v58
	v_mov_b32_e32 v58, v63
	v_mov_b32_e32 v62, v48
	v_mov_b32_e32 v63, v52
	v_mov_b32_e32 v52, v49
	v_add_u32_e32 v212, 0x90, v152
	v_ashrrev_i32_e32 v213, 31, v212
	v_lshlrev_b64 v[212:213], 6, v[212:213]
	v_lshl_add_u64 v[212:213], s[74:75], 0, v[212:213]
	global_load_dwordx4 v[196:199], v[212:213], off
	global_load_dwordx4 v[200:203], v[212:213], off offset:16
	global_load_dwordx4 v[204:207], v[212:213], off offset:32
	global_load_dwordx4 v[208:211], v[212:213], off offset:48
	global_store_dwordx4 v[226:227], v[220:223], off
	s_waitcnt vmcnt(7)
	v_pk_add_f32 v[180:181], v[180:181], v[182:183]
	v_pk_add_f32 v[184:185], v[184:185], v[186:187]
	s_waitcnt vmcnt(5)
	v_pk_add_f32 v[188:189], v[188:189], v[190:191]
	v_pk_add_f32 v[192:193], v[192:193], v[194:195]
	v_pk_add_f32 v[180:181], v[180:181], v[184:185]
	v_pk_add_f32 v[188:189], v[188:189], v[192:193]
	v_mul_f32_e32 v82, v82, v83
	v_mul_f32_e32 v56, v56, v57
	v_mul_f32_e32 v60, v60, v61
	v_mul_f32_e32 v52, v52, v53
	v_pk_add_f32 v[180:181], v[180:181], v[188:189]
	v_mul_f32_e32 v50, v50, v54
	v_mul_f32_e32 v58, v58, v59
	v_mul_f32_e32 v62, v62, v63
	v_mul_f32_e32 v51, v51, v55
	v_add_f32_e32 v180, v180, v181
	v_fmamk_f32 v180, v180, 0x3a800000, v160
	v_rsq_f32_e32 v181, v180
	s_nop 0
	v_mul_f32_e32 v181, 0xbfb8aa3b, v181
	v_mul_f32_e32 v83, v181, v83
	v_mul_f32_e32 v57, v181, v57
	v_mul_f32_e32 v61, v181, v61
	v_mul_f32_e32 v53, v181, v53
	v_mul_f32_e32 v54, v181, v54
	v_mul_f32_e32 v59, v181, v59
	v_mul_f32_e32 v63, v181, v63
	v_mul_f32_e32 v55, v181, v55
	v_exp_f32_e32 v83, v83
	v_exp_f32_e32 v57, v57
	v_exp_f32_e32 v61, v61
	v_exp_f32_e32 v53, v53
	v_exp_f32_e32 v54, v54
	v_exp_f32_e32 v59, v59
	v_exp_f32_e32 v63, v63
	v_exp_f32_e32 v55, v55
	v_fma_f32 v83, v83, v180, v180
	v_fma_f32 v57, v57, v180, v180
	v_fma_f32 v61, v61, v180, v180
	v_fma_f32 v53, v53, v180, v180
	v_fma_f32 v54, v54, v180, v180
	v_fma_f32 v59, v59, v180, v180
	v_fma_f32 v63, v63, v180, v180
	v_fma_f32 v55, v55, v180, v180
	v_rcp_f32_e32 v83, v83
	v_rcp_f32_e32 v57, v57
	v_rcp_f32_e32 v61, v61
	v_rcp_f32_e32 v53, v53
	v_rcp_f32_e32 v54, v54
	v_rcp_f32_e32 v59, v59
	v_rcp_f32_e32 v63, v63
	v_rcp_f32_e32 v55, v55
	v_mul_f32_e32 v82, v82, v83
	v_mul_f32_e32 v56, v56, v57
	v_mul_f32_e32 v60, v60, v61
	v_mul_f32_e32 v52, v52, v53
	v_mul_f32_e32 v50, v50, v54
	v_mul_f32_e32 v58, v58, v59
	v_mul_f32_e32 v62, v62, v63
	v_mul_f32_e32 v51, v51, v55
	v_cvt_pk_bf16_f32 v216, v82, v56
	v_cvt_pk_bf16_f32 v217, v60, v58
	v_cvt_pk_bf16_f32 v218, v62, v52
	v_cvt_pk_bf16_f32 v219, v50, v51
	v_mad_i64_i32 v[52:53], s[26:27], v80, s51, v[120:121]
	v_lshl_add_u64 v[52:53], v[52:53], 0, s[24:25]
	v_lshl_add_u64 v[52:53], v[52:53], 0, s[6:7]
	v_add_u32_e32 v64, 0x90, v152
	v_lshl_add_u64 v[52:53], v[52:53], 0, v[136:137]
	v_ashrrev_i32_e32 v65, 31, v64
	v_mov_b32_e32 v224, v52
	v_mov_b32_e32 v225, v53
	v_mov_b32_e32 v66, v44
	v_mov_b32_e32 v67, v40
	v_lshlrev_b64 v[48:49], 6, v[64:65]
	v_lshl_add_u64 v[60:61], s[74:75], 0, v[48:49]
	s_nop 0
	v_mov_b32_e32 v40, v45
	v_mov_b32_e32 v44, v46
	v_mov_b32_e32 v45, v42
	v_mov_b32_e32 v42, v47
	v_mov_b32_e32 v46, v32
	v_mov_b32_e32 v47, v36
	v_mov_b32_e32 v36, v33
	v_add_u32_e32 v212, 0xa0, v152
	v_ashrrev_i32_e32 v213, 31, v212
	v_lshlrev_b64 v[212:213], 6, v[212:213]
	v_lshl_add_u64 v[212:213], s[74:75], 0, v[212:213]
	global_load_dwordx4 v[180:183], v[212:213], off
	global_load_dwordx4 v[184:187], v[212:213], off offset:16
	global_load_dwordx4 v[188:191], v[212:213], off offset:32
	global_load_dwordx4 v[192:195], v[212:213], off offset:48
	global_store_dwordx4 v[224:225], v[216:219], off
	s_waitcnt vmcnt(7)
	v_pk_add_f32 v[196:197], v[196:197], v[198:199]
	v_pk_add_f32 v[200:201], v[200:201], v[202:203]
	s_waitcnt vmcnt(5)
	v_pk_add_f32 v[204:205], v[204:205], v[206:207]
	v_pk_add_f32 v[208:209], v[208:209], v[210:211]
	v_pk_add_f32 v[196:197], v[196:197], v[200:201]
	v_pk_add_f32 v[204:205], v[204:205], v[208:209]
	v_mul_f32_e32 v66, v66, v67
	v_mul_f32_e32 v40, v40, v41
	v_mul_f32_e32 v44, v44, v45
	v_mul_f32_e32 v36, v36, v37
	v_pk_add_f32 v[196:197], v[196:197], v[204:205]
	v_mul_f32_e32 v34, v34, v38
	v_mul_f32_e32 v42, v42, v43
	v_mul_f32_e32 v46, v46, v47
	v_mul_f32_e32 v35, v35, v39
	v_add_f32_e32 v196, v196, v197
	v_fmamk_f32 v196, v196, 0x3a800000, v160
	v_rsq_f32_e32 v197, v196
	s_nop 0
	v_mul_f32_e32 v197, 0xbfb8aa3b, v197
	v_mul_f32_e32 v67, v197, v67
	v_mul_f32_e32 v41, v197, v41
	v_mul_f32_e32 v45, v197, v45
	v_mul_f32_e32 v37, v197, v37
	v_mul_f32_e32 v38, v197, v38
	v_mul_f32_e32 v43, v197, v43
	v_mul_f32_e32 v47, v197, v47
	v_mul_f32_e32 v39, v197, v39
	v_exp_f32_e32 v67, v67
	v_exp_f32_e32 v41, v41
	v_exp_f32_e32 v45, v45
	v_exp_f32_e32 v37, v37
	v_exp_f32_e32 v38, v38
	v_exp_f32_e32 v43, v43
	v_exp_f32_e32 v47, v47
	v_exp_f32_e32 v39, v39
	v_fma_f32 v67, v67, v196, v196
	v_fma_f32 v41, v41, v196, v196
	v_fma_f32 v45, v45, v196, v196
	v_fma_f32 v37, v37, v196, v196
	v_fma_f32 v38, v38, v196, v196
	v_fma_f32 v43, v43, v196, v196
	v_fma_f32 v47, v47, v196, v196
	v_fma_f32 v39, v39, v196, v196
	v_rcp_f32_e32 v67, v67
	v_rcp_f32_e32 v41, v41
	v_rcp_f32_e32 v45, v45
	v_rcp_f32_e32 v37, v37
	v_rcp_f32_e32 v38, v38
	v_rcp_f32_e32 v43, v43
	v_rcp_f32_e32 v47, v47
	v_rcp_f32_e32 v39, v39
	v_mul_f32_e32 v66, v66, v67
	v_mul_f32_e32 v40, v40, v41
	v_mul_f32_e32 v44, v44, v45
	v_mul_f32_e32 v36, v36, v37
	v_mul_f32_e32 v34, v34, v38
	v_mul_f32_e32 v42, v42, v43
	v_mul_f32_e32 v46, v46, v47
	v_mul_f32_e32 v35, v35, v39
	v_cvt_pk_bf16_f32 v220, v66, v40
	v_cvt_pk_bf16_f32 v221, v44, v42
	v_cvt_pk_bf16_f32 v222, v46, v36
	v_cvt_pk_bf16_f32 v223, v34, v35
	v_mad_i64_i32 v[36:37], s[26:27], v64, s51, v[120:121]
	v_lshl_add_u64 v[36:37], v[36:37], 0, s[24:25]
	v_lshl_add_u64 v[36:37], v[36:37], 0, s[6:7]
	v_add_u32_e32 v48, 0xa0, v152
	v_lshl_add_u64 v[36:37], v[36:37], 0, v[136:137]
	v_ashrrev_i32_e32 v49, 31, v48
	v_mov_b32_e32 v226, v36
	v_mov_b32_e32 v227, v37
	v_mov_b32_e32 v50, v28
	v_mov_b32_e32 v51, v24
	v_lshlrev_b64 v[32:33], 6, v[48:49]
	v_lshl_add_u64 v[44:45], s[74:75], 0, v[32:33]
	s_nop 0
	v_mov_b32_e32 v24, v29
	v_mov_b32_e32 v28, v30
	v_mov_b32_e32 v29, v26
	v_mov_b32_e32 v26, v31
	v_mov_b32_e32 v30, v16
	v_mov_b32_e32 v31, v20
	v_mov_b32_e32 v20, v17
	v_add_u32_e32 v212, 0xb0, v152
	v_ashrrev_i32_e32 v213, 31, v212
	v_lshlrev_b64 v[212:213], 6, v[212:213]
	v_lshl_add_u64 v[212:213], s[74:75], 0, v[212:213]
	global_load_dwordx4 v[196:199], v[212:213], off
	global_load_dwordx4 v[200:203], v[212:213], off offset:16
	global_load_dwordx4 v[204:207], v[212:213], off offset:32
	global_load_dwordx4 v[208:211], v[212:213], off offset:48
	global_store_dwordx4 v[226:227], v[220:223], off
	s_waitcnt vmcnt(7)
	v_pk_add_f32 v[180:181], v[180:181], v[182:183]
	v_pk_add_f32 v[184:185], v[184:185], v[186:187]
	s_waitcnt vmcnt(5)
	v_pk_add_f32 v[188:189], v[188:189], v[190:191]
	v_pk_add_f32 v[192:193], v[192:193], v[194:195]
	v_pk_add_f32 v[180:181], v[180:181], v[184:185]
	v_pk_add_f32 v[188:189], v[188:189], v[192:193]
	v_mul_f32_e32 v50, v50, v51
	v_mul_f32_e32 v24, v24, v25
	v_mul_f32_e32 v28, v28, v29
	v_mul_f32_e32 v20, v20, v21
	v_pk_add_f32 v[180:181], v[180:181], v[188:189]
	v_mul_f32_e32 v18, v18, v22
	v_mul_f32_e32 v26, v26, v27
	v_mul_f32_e32 v30, v30, v31
	v_mul_f32_e32 v19, v19, v23
	v_add_f32_e32 v180, v180, v181
	v_fmamk_f32 v180, v180, 0x3a800000, v160
	v_rsq_f32_e32 v181, v180
	s_nop 0
	v_mul_f32_e32 v181, 0xbfb8aa3b, v181
	v_mul_f32_e32 v51, v181, v51
	v_mul_f32_e32 v25, v181, v25
	v_mul_f32_e32 v29, v181, v29
	v_mul_f32_e32 v21, v181, v21
	v_mul_f32_e32 v22, v181, v22
	v_mul_f32_e32 v27, v181, v27
	v_mul_f32_e32 v31, v181, v31
	v_mul_f32_e32 v23, v181, v23
	v_exp_f32_e32 v51, v51
	v_exp_f32_e32 v25, v25
	v_exp_f32_e32 v29, v29
	v_exp_f32_e32 v21, v21
	v_exp_f32_e32 v22, v22
	v_exp_f32_e32 v27, v27
	v_exp_f32_e32 v31, v31
	v_exp_f32_e32 v23, v23
	v_fma_f32 v51, v51, v180, v180
	v_fma_f32 v25, v25, v180, v180
	v_fma_f32 v29, v29, v180, v180
	v_fma_f32 v21, v21, v180, v180
	v_fma_f32 v22, v22, v180, v180
	v_fma_f32 v27, v27, v180, v180
	v_fma_f32 v31, v31, v180, v180
	v_fma_f32 v23, v23, v180, v180
	v_rcp_f32_e32 v51, v51
	v_rcp_f32_e32 v25, v25
	v_rcp_f32_e32 v29, v29
	v_rcp_f32_e32 v21, v21
	v_rcp_f32_e32 v22, v22
	v_rcp_f32_e32 v27, v27
	v_rcp_f32_e32 v31, v31
	v_rcp_f32_e32 v23, v23
	v_mul_f32_e32 v50, v50, v51
	v_mul_f32_e32 v24, v24, v25
	v_mul_f32_e32 v28, v28, v29
	v_mul_f32_e32 v20, v20, v21
	v_mul_f32_e32 v18, v18, v22
	v_mul_f32_e32 v26, v26, v27
	v_mul_f32_e32 v30, v30, v31
	v_mul_f32_e32 v19, v19, v23
	v_cvt_pk_bf16_f32 v216, v50, v24
	v_cvt_pk_bf16_f32 v217, v28, v26
	v_cvt_pk_bf16_f32 v218, v30, v20
	v_cvt_pk_bf16_f32 v219, v18, v19
	v_mad_i64_i32 v[20:21], s[26:27], v48, s51, v[120:121]
	v_lshl_add_u64 v[20:21], v[20:21], 0, s[24:25]
	v_lshl_add_u64 v[20:21], v[20:21], 0, s[6:7]
	v_add_u32_e32 v32, 0xb0, v152
	v_lshl_add_u64 v[20:21], v[20:21], 0, v[136:137]
	v_ashrrev_i32_e32 v33, 31, v32
	v_mov_b32_e32 v224, v20
	v_mov_b32_e32 v225, v21
	v_mov_b32_e32 v34, v12
	v_mov_b32_e32 v35, v8
	v_lshlrev_b64 v[16:17], 6, v[32:33]
	v_lshl_add_u64 v[28:29], s[74:75], 0, v[16:17]
	s_nop 0
	v_mov_b32_e32 v8, v13
	v_mov_b32_e32 v12, v14
	v_mov_b32_e32 v13, v10
	v_mov_b32_e32 v10, v15
	v_mov_b32_e32 v14, v0
	v_mov_b32_e32 v15, v4
	v_mov_b32_e32 v4, v1
	global_store_dwordx4 v[224:225], v[216:219], off
	s_waitcnt vmcnt(3)
	v_pk_add_f32 v[196:197], v[196:197], v[198:199]
	v_pk_add_f32 v[200:201], v[200:201], v[202:203]
	s_waitcnt vmcnt(1)
	v_pk_add_f32 v[204:205], v[204:205], v[206:207]
	v_pk_add_f32 v[208:209], v[208:209], v[210:211]
	v_pk_add_f32 v[196:197], v[196:197], v[200:201]
	v_pk_add_f32 v[204:205], v[204:205], v[208:209]
	v_mul_f32_e32 v34, v34, v35
	v_mul_f32_e32 v8, v8, v9
	v_mul_f32_e32 v12, v12, v13
	v_mul_f32_e32 v4, v4, v5
	v_pk_add_f32 v[196:197], v[196:197], v[204:205]
	v_mul_f32_e32 v2, v2, v6
	v_mul_f32_e32 v10, v10, v11
	v_mul_f32_e32 v14, v14, v15
	v_mul_f32_e32 v3, v3, v7
	v_add_f32_e32 v196, v196, v197
	v_fmamk_f32 v196, v196, 0x3a800000, v160
	v_rsq_f32_e32 v197, v196
	s_nop 0
	v_mul_f32_e32 v197, 0xbfb8aa3b, v197
	v_mul_f32_e32 v35, v197, v35
	v_mul_f32_e32 v9, v197, v9
	v_mul_f32_e32 v13, v197, v13
	v_mul_f32_e32 v5, v197, v5
	v_mul_f32_e32 v6, v197, v6
	v_mul_f32_e32 v11, v197, v11
	v_mul_f32_e32 v15, v197, v15
	v_mul_f32_e32 v7, v197, v7
	v_exp_f32_e32 v35, v35
	v_exp_f32_e32 v9, v9
	v_exp_f32_e32 v13, v13
	v_exp_f32_e32 v5, v5
	v_exp_f32_e32 v6, v6
	v_exp_f32_e32 v11, v11
	v_exp_f32_e32 v15, v15
	v_exp_f32_e32 v7, v7
	v_fma_f32 v35, v35, v196, v196
	v_fma_f32 v9, v9, v196, v196
	v_fma_f32 v13, v13, v196, v196
	v_fma_f32 v5, v5, v196, v196
	v_fma_f32 v6, v6, v196, v196
	v_fma_f32 v11, v11, v196, v196
	v_fma_f32 v15, v15, v196, v196
	v_fma_f32 v7, v7, v196, v196
	v_rcp_f32_e32 v35, v35
	v_rcp_f32_e32 v9, v9
	v_rcp_f32_e32 v13, v13
	v_rcp_f32_e32 v5, v5
	v_rcp_f32_e32 v6, v6
	v_rcp_f32_e32 v11, v11
	v_rcp_f32_e32 v15, v15
	v_rcp_f32_e32 v7, v7
	v_mul_f32_e32 v34, v34, v35
	v_mul_f32_e32 v8, v8, v9
	v_mul_f32_e32 v12, v12, v13
	v_mul_f32_e32 v4, v4, v5
	v_mul_f32_e32 v2, v2, v6
	v_mul_f32_e32 v10, v10, v11
	v_mul_f32_e32 v14, v14, v15
	v_mul_f32_e32 v3, v3, v7
	v_cvt_pk_bf16_f32 v220, v34, v8
	v_cvt_pk_bf16_f32 v221, v12, v10
	v_cvt_pk_bf16_f32 v222, v14, v4
	v_cvt_pk_bf16_f32 v223, v2, v3
	v_mad_i64_i32 v[4:5], s[26:27], v32, s51, v[120:121]
	v_lshl_add_u64 v[4:5], v[4:5], 0, s[24:25]
	v_lshl_add_u64 v[4:5], v[4:5], 0, s[6:7]
	v_lshl_add_u64 v[4:5], v[4:5], 0, v[136:137]
	global_store_dwordx4 v[4:5], v[220:223], off
	s_nop 1
	s_andn2_b64 vcc, exec, s[4:5]
	s_mov_b64 s[4:5], -1
	s_cbranch_vccnz .LBB0_157
	s_branch .LBB0_191

.LBB0_981:
	v_ashrrev_i32_e32 v153, 31, v152
	v_lshlrev_b64 v[154:155], 6, v[152:153]
	v_lshl_add_u64 v[170:171], s[74:75], 0, v[154:155]
	s_waitcnt lgkmcnt(0)
	s_nop 0
	v_mov_b32_e32 v174, v124
	v_mov_b32_e32 v175, v116
	v_mov_b32_e32 v116, v125
	v_mov_b32_e32 v124, v126
	v_mov_b32_e32 v125, v118
	v_mov_b32_e32 v118, v127
	v_mov_b32_e32 v126, v120
	v_mov_b32_e32 v127, v112
	v_mov_b32_e32 v112, v121
	v_mov_b32_e32 v176, v122
	v_mov_b32_e32 v177, v114
	v_mov_b32_e32 v114, v123
	s_lshl_b32 s26, s26, 7
	v_mov_b64_e32 v[120:121], s[72:73]
	s_ashr_i32 s27, s26, 31
	v_mad_i64_i32 v[122:123], s[28:29], v152, s53, v[120:121]
	s_lshl_b64 s[26:27], s[26:27], 1
	v_lshl_add_u64 v[122:123], v[122:123], 0, s[26:27]
	v_lshl_add_u64 v[122:123], v[122:123], 0, s[8:9]
	v_mov_b32_e32 v212, v152
	v_ashrrev_i32_e32 v213, 31, v212
	v_lshlrev_b64 v[212:213], 6, v[212:213]
	v_lshl_add_u64 v[212:213], s[74:75], 0, v[212:213]
	global_load_dwordx4 v[180:183], v[212:213], off
	global_load_dwordx4 v[184:187], v[212:213], off offset:16
	global_load_dwordx4 v[188:191], v[212:213], off offset:32
	global_load_dwordx4 v[192:195], v[212:213], off offset:48
	v_or_b32_e32 v212, 16, v152
	v_ashrrev_i32_e32 v213, 31, v212
	v_lshlrev_b64 v[212:213], 6, v[212:213]
	v_lshl_add_u64 v[212:213], s[74:75], 0, v[212:213]
	global_load_dwordx4 v[196:199], v[212:213], off
	global_load_dwordx4 v[200:203], v[212:213], off offset:16
	global_load_dwordx4 v[204:207], v[212:213], off offset:32
	global_load_dwordx4 v[208:211], v[212:213], off offset:48
	s_waitcnt vmcnt(6)
	v_pk_add_f32 v[180:181], v[180:181], v[182:183]
	v_pk_add_f32 v[184:185], v[184:185], v[186:187]
	s_waitcnt vmcnt(4)
	v_pk_add_f32 v[188:189], v[188:189], v[190:191]
	v_pk_add_f32 v[192:193], v[192:193], v[194:195]
	v_pk_add_f32 v[180:181], v[180:181], v[184:185]
	v_pk_add_f32 v[188:189], v[188:189], v[192:193]
	v_mul_f32_e32 v116, v116, v117
	v_mul_f32_e32 v124, v124, v125
	v_mul_f32_e32 v118, v118, v119
	v_mul_f32_e32 v126, v126, v127
	v_pk_add_f32 v[180:181], v[180:181], v[188:189]
	v_mul_f32_e32 v174, v174, v175
	v_mul_f32_e32 v112, v112, v113
	v_mul_f32_e32 v176, v176, v177
	v_mul_f32_e32 v114, v114, v115
	v_add_f32_e32 v180, v180, v181
	v_fmamk_f32 v180, v180, 0x3a800000, v160
	v_rsq_f32_e32 v181, v180
	s_nop 0
	v_mul_f32_e32 v181, 0xbfb8aa3b, v181
	v_mul_f32_e32 v117, v181, v117
	v_mul_f32_e32 v125, v181, v125
	v_mul_f32_e32 v119, v181, v119
	v_mul_f32_e32 v127, v181, v127
	v_mul_f32_e32 v175, v181, v175
	v_mul_f32_e32 v113, v181, v113
	v_mul_f32_e32 v177, v181, v177
	v_mul_f32_e32 v115, v181, v115
	v_exp_f32_e32 v117, v117
	v_exp_f32_e32 v125, v125
	v_exp_f32_e32 v119, v119
	v_exp_f32_e32 v127, v127
	v_exp_f32_e32 v175, v175
	v_exp_f32_e32 v113, v113
	v_exp_f32_e32 v177, v177
	v_exp_f32_e32 v115, v115
	v_fma_f32 v117, v117, v180, v180
	v_fma_f32 v125, v125, v180, v180
	v_fma_f32 v119, v119, v180, v180
	v_fma_f32 v127, v127, v180, v180
	v_fma_f32 v175, v175, v180, v180
	v_fma_f32 v113, v113, v180, v180
	v_fma_f32 v177, v177, v180, v180
	v_fma_f32 v115, v115, v180, v180
	v_rcp_f32_e32 v117, v117
	v_rcp_f32_e32 v125, v125
	v_rcp_f32_e32 v119, v119
	v_rcp_f32_e32 v127, v127
	v_rcp_f32_e32 v175, v175
	v_rcp_f32_e32 v113, v113
	v_rcp_f32_e32 v177, v177
	v_rcp_f32_e32 v115, v115
	v_mul_f32_e32 v116, v116, v117
	v_mul_f32_e32 v124, v124, v125
	v_mul_f32_e32 v118, v118, v119
	v_mul_f32_e32 v126, v126, v127
	v_mul_f32_e32 v174, v174, v175
	v_mul_f32_e32 v112, v112, v113
	v_mul_f32_e32 v176, v176, v177
	v_mul_f32_e32 v114, v114, v115
	v_cvt_pk_bf16_f32 v216, v174, v116
	v_cvt_pk_bf16_f32 v217, v124, v118
	v_cvt_pk_bf16_f32 v218, v126, v112
	v_cvt_pk_bf16_f32 v219, v176, v114
	v_or_b32_e32 v126, 16, v152
	v_lshl_add_u64 v[116:117], v[122:123], 0, v[136:137]
	v_ashrrev_i32_e32 v127, 31, v126
	v_mov_b32_e32 v224, v116
	v_mov_b32_e32 v225, v117
	v_mov_b32_e32 v162, v108
	v_mov_b32_e32 v163, v100
	v_lshlrev_b64 v[112:113], 6, v[126:127]
	v_lshl_add_u64 v[154:155], s[74:75], 0, v[112:113]
	s_nop 0
	v_mov_b32_e32 v100, v109
	v_mov_b32_e32 v108, v110
	v_mov_b32_e32 v109, v102
	v_mov_b32_e32 v102, v111
	v_mov_b32_e32 v110, v104
	v_mov_b32_e32 v111, v96
	v_mov_b32_e32 v96, v105
	v_mov_b32_e32 v104, v106
	v_mov_b32_e32 v105, v98
	v_mov_b32_e32 v98, v107
	v_or_b32_e32 v212, 32, v152
	v_ashrrev_i32_e32 v213, 31, v212
	v_lshlrev_b64 v[212:213], 6, v[212:213]
	v_lshl_add_u64 v[212:213], s[74:75], 0, v[212:213]
	global_load_dwordx4 v[180:183], v[212:213], off
	global_load_dwordx4 v[184:187], v[212:213], off offset:16
	global_load_dwordx4 v[188:191], v[212:213], off offset:32
	global_load_dwordx4 v[192:195], v[212:213], off offset:48
	global_store_dwordx4 v[224:225], v[216:219], off
	s_waitcnt vmcnt(7)
	v_pk_add_f32 v[196:197], v[196:197], v[198:199]
	v_pk_add_f32 v[200:201], v[200:201], v[202:203]
	s_waitcnt vmcnt(5)
	v_pk_add_f32 v[204:205], v[204:205], v[206:207]
	v_pk_add_f32 v[208:209], v[208:209], v[210:211]
	v_pk_add_f32 v[196:197], v[196:197], v[200:201]
	v_pk_add_f32 v[204:205], v[204:205], v[208:209]
	v_mul_f32_e32 v100, v100, v101
	v_mul_f32_e32 v108, v108, v109
	v_mul_f32_e32 v162, v162, v163
	v_mul_f32_e32 v102, v102, v103
	v_pk_add_f32 v[196:197], v[196:197], v[204:205]
	v_mul_f32_e32 v110, v110, v111
	v_mul_f32_e32 v96, v96, v97
	v_mul_f32_e32 v104, v104, v105
	v_mul_f32_e32 v98, v98, v99
	v_add_f32_e32 v196, v196, v197
	v_fmamk_f32 v196, v196, 0x3a800000, v160
	v_rsq_f32_e32 v197, v196
	s_nop 0
	v_mul_f32_e32 v197, 0xbfb8aa3b, v197
	v_mul_f32_e32 v101, v197, v101
	v_mul_f32_e32 v109, v197, v109
	v_mul_f32_e32 v163, v197, v163
	v_mul_f32_e32 v103, v197, v103
	v_mul_f32_e32 v111, v197, v111
	v_mul_f32_e32 v97, v197, v97
	v_mul_f32_e32 v105, v197, v105
	v_mul_f32_e32 v99, v197, v99
	v_exp_f32_e32 v101, v101
	v_exp_f32_e32 v109, v109
	v_exp_f32_e32 v163, v163
	v_exp_f32_e32 v103, v103
	v_exp_f32_e32 v111, v111
	v_exp_f32_e32 v97, v97
	v_exp_f32_e32 v105, v105
	v_exp_f32_e32 v99, v99
	v_fma_f32 v101, v101, v196, v196
	v_fma_f32 v109, v109, v196, v196
	v_fma_f32 v163, v163, v196, v196
	v_fma_f32 v103, v103, v196, v196
	v_fma_f32 v111, v111, v196, v196
	v_fma_f32 v97, v97, v196, v196
	v_fma_f32 v105, v105, v196, v196
	v_fma_f32 v99, v99, v196, v196
	v_rcp_f32_e32 v101, v101
	v_rcp_f32_e32 v109, v109
	v_rcp_f32_e32 v163, v163
	v_rcp_f32_e32 v103, v103
	v_rcp_f32_e32 v111, v111
	v_rcp_f32_e32 v97, v97
	v_rcp_f32_e32 v105, v105
	v_rcp_f32_e32 v99, v99
	v_mul_f32_e32 v100, v100, v101
	v_mul_f32_e32 v108, v108, v109
	v_mul_f32_e32 v162, v162, v163
	v_mul_f32_e32 v102, v102, v103
	v_mul_f32_e32 v110, v110, v111
	v_mul_f32_e32 v96, v96, v97
	v_mul_f32_e32 v104, v104, v105
	v_mul_f32_e32 v98, v98, v99
	v_cvt_pk_bf16_f32 v220, v162, v100
	v_cvt_pk_bf16_f32 v221, v108, v102
	v_cvt_pk_bf16_f32 v222, v110, v96
	v_cvt_pk_bf16_f32 v223, v104, v98
	v_mad_i64_i32 v[112:113], s[28:29], v126, s53, v[120:121]
	v_lshl_add_u64 v[112:113], v[112:113], 0, s[26:27]
	v_lshl_add_u64 v[100:101], v[112:113], 0, s[8:9]
	v_or_b32_e32 v112, 32, v152
	v_lshl_add_u64 v[100:101], v[100:101], 0, v[136:137]
	v_ashrrev_i32_e32 v113, 31, v112
	v_mov_b32_e32 v226, v100
	v_mov_b32_e32 v227, v101
	v_mov_b32_e32 v114, v92
	v_mov_b32_e32 v92, v94
	v_lshlrev_b64 v[96:97], 6, v[112:113]
	v_lshl_add_u64 v[108:109], s[74:75], 0, v[96:97]
	s_nop 0
	v_mov_b32_e32 v94, v80
	v_mov_b32_e32 v80, v82
	v_mov_b32_e32 v115, v88
	v_mov_b32_e32 v88, v93
	v_mov_b32_e32 v93, v90
	v_mov_b32_e32 v90, v95
	v_mov_b32_e32 v95, v84
	v_mov_b32_e32 v84, v81
	v_mov_b32_e32 v81, v86
	v_mov_b32_e32 v86, v83
	v_or_b32_e32 v212, 48, v152
	v_ashrrev_i32_e32 v213, 31, v212
	v_lshlrev_b64 v[212:213], 6, v[212:213]
	v_lshl_add_u64 v[212:213], s[74:75], 0, v[212:213]
	global_load_dwordx4 v[196:199], v[212:213], off
	global_load_dwordx4 v[200:203], v[212:213], off offset:16
	global_load_dwordx4 v[204:207], v[212:213], off offset:32
	global_load_dwordx4 v[208:211], v[212:213], off offset:48
	global_store_dwordx4 v[226:227], v[220:223], off
	s_waitcnt vmcnt(7)
	v_pk_add_f32 v[180:181], v[180:181], v[182:183]
	v_pk_add_f32 v[184:185], v[184:185], v[186:187]
	s_waitcnt vmcnt(5)
	v_pk_add_f32 v[188:189], v[188:189], v[190:191]
	v_pk_add_f32 v[192:193], v[192:193], v[194:195]
	v_pk_add_f32 v[180:181], v[180:181], v[184:185]
	v_pk_add_f32 v[188:189], v[188:189], v[192:193]
	v_mul_f32_e32 v114, v114, v115
	v_mul_f32_e32 v88, v88, v89
	v_mul_f32_e32 v92, v92, v93
	v_mul_f32_e32 v90, v90, v91
	v_pk_add_f32 v[180:181], v[180:181], v[188:189]
	v_mul_f32_e32 v94, v94, v95
	v_mul_f32_e32 v84, v84, v85
	v_mul_f32_e32 v80, v80, v81
	v_mul_f32_e32 v86, v86, v87
	v_add_f32_e32 v180, v180, v181
	v_fmamk_f32 v180, v180, 0x3a800000, v160
	v_rsq_f32_e32 v181, v180
	s_nop 0
	v_mul_f32_e32 v181, 0xbfb8aa3b, v181
	v_mul_f32_e32 v115, v181, v115
	v_mul_f32_e32 v89, v181, v89
	v_mul_f32_e32 v93, v181, v93
	v_mul_f32_e32 v91, v181, v91
	v_mul_f32_e32 v95, v181, v95
	v_mul_f32_e32 v85, v181, v85
	v_mul_f32_e32 v81, v181, v81
	v_mul_f32_e32 v87, v181, v87
	v_exp_f32_e32 v115, v115
	v_exp_f32_e32 v89, v89
	v_exp_f32_e32 v93, v93
	v_exp_f32_e32 v91, v91
	v_exp_f32_e32 v95, v95
	v_exp_f32_e32 v85, v85
	v_exp_f32_e32 v81, v81
	v_exp_f32_e32 v87, v87
	v_fma_f32 v115, v115, v180, v180
	v_fma_f32 v89, v89, v180, v180
	v_fma_f32 v93, v93, v180, v180
	v_fma_f32 v91, v91, v180, v180
	v_fma_f32 v95, v95, v180, v180
	v_fma_f32 v85, v85, v180, v180
	v_fma_f32 v81, v81, v180, v180
	v_fma_f32 v87, v87, v180, v180
	v_rcp_f32_e32 v115, v115
	v_rcp_f32_e32 v89, v89
	v_rcp_f32_e32 v93, v93
	v_rcp_f32_e32 v91, v91
	v_rcp_f32_e32 v95, v95
	v_rcp_f32_e32 v85, v85
	v_rcp_f32_e32 v81, v81
	v_rcp_f32_e32 v87, v87
	v_mul_f32_e32 v114, v114, v115
	v_mul_f32_e32 v88, v88, v89
	v_mul_f32_e32 v92, v92, v93
	v_mul_f32_e32 v90, v90, v91
	v_mul_f32_e32 v94, v94, v95
	v_mul_f32_e32 v84, v84, v85
	v_mul_f32_e32 v80, v80, v81
	v_mul_f32_e32 v86, v86, v87
	v_cvt_pk_bf16_f32 v216, v114, v88
	v_cvt_pk_bf16_f32 v217, v92, v90
	v_cvt_pk_bf16_f32 v218, v94, v84
	v_cvt_pk_bf16_f32 v219, v80, v86
	v_mad_i64_i32 v[96:97], s[28:29], v112, s53, v[120:121]
	v_lshl_add_u64 v[84:85], v[96:97], 0, s[26:27]
	v_lshl_add_u64 v[84:85], v[84:85], 0, s[8:9]
	v_or_b32_e32 v96, 48, v152
	v_lshl_add_u64 v[84:85], v[84:85], 0, v[136:137]
	v_ashrrev_i32_e32 v97, 31, v96
	v_mov_b32_e32 v224, v84
	v_mov_b32_e32 v225, v85
	v_mov_b32_e32 v98, v76
	v_mov_b32_e32 v99, v72
	v_lshlrev_b64 v[80:81], 6, v[96:97]
	v_lshl_add_u64 v[92:93], s[74:75], 0, v[80:81]
	s_nop 0
	v_mov_b32_e32 v72, v77
	v_mov_b32_e32 v76, v78
	v_mov_b32_e32 v77, v74
	v_mov_b32_e32 v74, v79
	v_mov_b32_e32 v78, v64
	v_mov_b32_e32 v79, v68
	v_mov_b32_e32 v68, v65
	v_add_u32_e32 v212, 0x80, v152
	v_ashrrev_i32_e32 v213, 31, v212
	v_lshlrev_b64 v[212:213], 6, v[212:213]
	v_lshl_add_u64 v[212:213], s[74:75], 0, v[212:213]
	global_load_dwordx4 v[180:183], v[212:213], off
	global_load_dwordx4 v[184:187], v[212:213], off offset:16
	global_load_dwordx4 v[188:191], v[212:213], off offset:32
	global_load_dwordx4 v[192:195], v[212:213], off offset:48
	global_store_dwordx4 v[224:225], v[216:219], off
	s_waitcnt vmcnt(7)
	v_pk_add_f32 v[196:197], v[196:197], v[198:199]
	v_pk_add_f32 v[200:201], v[200:201], v[202:203]
	s_waitcnt vmcnt(5)
	v_pk_add_f32 v[204:205], v[204:205], v[206:207]
	v_pk_add_f32 v[208:209], v[208:209], v[210:211]
	v_pk_add_f32 v[196:197], v[196:197], v[200:201]
	v_pk_add_f32 v[204:205], v[204:205], v[208:209]
	v_mul_f32_e32 v98, v98, v99
	v_mul_f32_e32 v72, v72, v73
	v_mul_f32_e32 v76, v76, v77
	v_mul_f32_e32 v68, v68, v69
	v_pk_add_f32 v[196:197], v[196:197], v[204:205]
	v_mul_f32_e32 v66, v66, v70
	v_mul_f32_e32 v74, v74, v75
	v_mul_f32_e32 v78, v78, v79
	v_mul_f32_e32 v67, v67, v71
	v_add_f32_e32 v196, v196, v197
	v_fmamk_f32 v196, v196, 0x3a800000, v160
	v_rsq_f32_e32 v197, v196
	s_nop 0
	v_mul_f32_e32 v197, 0xbfb8aa3b, v197
	v_mul_f32_e32 v99, v197, v99
	v_mul_f32_e32 v73, v197, v73
	v_mul_f32_e32 v77, v197, v77
	v_mul_f32_e32 v69, v197, v69
	v_mul_f32_e32 v70, v197, v70
	v_mul_f32_e32 v75, v197, v75
	v_mul_f32_e32 v79, v197, v79
	v_mul_f32_e32 v71, v197, v71
	v_exp_f32_e32 v99, v99
	v_exp_f32_e32 v73, v73
	v_exp_f32_e32 v77, v77
	v_exp_f32_e32 v69, v69
	v_exp_f32_e32 v70, v70
	v_exp_f32_e32 v75, v75
	v_exp_f32_e32 v79, v79
	v_exp_f32_e32 v71, v71
	v_fma_f32 v99, v99, v196, v196
	v_fma_f32 v73, v73, v196, v196
	v_fma_f32 v77, v77, v196, v196
	v_fma_f32 v69, v69, v196, v196
	v_fma_f32 v70, v70, v196, v196
	v_fma_f32 v75, v75, v196, v196
	v_fma_f32 v79, v79, v196, v196
	v_fma_f32 v71, v71, v196, v196
	v_rcp_f32_e32 v99, v99
	v_rcp_f32_e32 v73, v73
	v_rcp_f32_e32 v77, v77
	v_rcp_f32_e32 v69, v69
	v_rcp_f32_e32 v70, v70
	v_rcp_f32_e32 v75, v75
	v_rcp_f32_e32 v79, v79
	v_rcp_f32_e32 v71, v71
	v_mul_f32_e32 v98, v98, v99
	v_mul_f32_e32 v72, v72, v73
	v_mul_f32_e32 v76, v76, v77
	v_mul_f32_e32 v68, v68, v69
	v_mul_f32_e32 v66, v66, v70
	v_mul_f32_e32 v74, v74, v75
	v_mul_f32_e32 v78, v78, v79
	v_mul_f32_e32 v67, v67, v71
	v_cvt_pk_bf16_f32 v220, v98, v72
	v_cvt_pk_bf16_f32 v221, v76, v74
	v_cvt_pk_bf16_f32 v222, v78, v68
	v_cvt_pk_bf16_f32 v223, v66, v67
	v_mad_i64_i32 v[68:69], s[28:29], v96, s53, v[120:121]
	v_lshl_add_u64 v[68:69], v[68:69], 0, s[26:27]
	v_lshl_add_u64 v[68:69], v[68:69], 0, s[8:9]
	v_add_u32_e32 v80, 0x80, v152
	v_lshl_add_u64 v[68:69], v[68:69], 0, v[136:137]
	v_ashrrev_i32_e32 v81, 31, v80
	v_mov_b32_e32 v226, v68
	v_mov_b32_e32 v227, v69
	v_mov_b32_e32 v82, v60
	v_mov_b32_e32 v83, v56
	v_lshlrev_b64 v[64:65], 6, v[80:81]
	v_lshl_add_u64 v[76:77], s[74:75], 0, v[64:65]
	s_nop 0
	v_mov_b32_e32 v56, v61
	v_mov_b32_e32 v60, v62
	v_mov_b32_e32 v61, v58
	v_mov_b32_e32 v58, v63
	v_mov_b32_e32 v62, v48
	v_mov_b32_e32 v63, v52
	v_mov_b32_e32 v52, v49
	v_add_u32_e32 v212, 0x90, v152
	v_ashrrev_i32_e32 v213, 31, v212
	v_lshlrev_b64 v[212:213], 6, v[212:213]
	v_lshl_add_u64 v[212:213], s[74:75], 0, v[212:213]
	global_load_dwordx4 v[196:199], v[212:213], off
	global_load_dwordx4 v[200:203], v[212:213], off offset:16
	global_load_dwordx4 v[204:207], v[212:213], off offset:32
	global_load_dwordx4 v[208:211], v[212:213], off offset:48
	global_store_dwordx4 v[226:227], v[220:223], off
	s_waitcnt vmcnt(7)
	v_pk_add_f32 v[180:181], v[180:181], v[182:183]
	v_pk_add_f32 v[184:185], v[184:185], v[186:187]
	s_waitcnt vmcnt(5)
	v_pk_add_f32 v[188:189], v[188:189], v[190:191]
	v_pk_add_f32 v[192:193], v[192:193], v[194:195]
	v_pk_add_f32 v[180:181], v[180:181], v[184:185]
	v_pk_add_f32 v[188:189], v[188:189], v[192:193]
	v_mul_f32_e32 v82, v82, v83
	v_mul_f32_e32 v56, v56, v57
	v_mul_f32_e32 v60, v60, v61
	v_mul_f32_e32 v52, v52, v53
	v_pk_add_f32 v[180:181], v[180:181], v[188:189]
	v_mul_f32_e32 v50, v50, v54
	v_mul_f32_e32 v58, v58, v59
	v_mul_f32_e32 v62, v62, v63
	v_mul_f32_e32 v51, v51, v55
	v_add_f32_e32 v180, v180, v181
	v_fmamk_f32 v180, v180, 0x3a800000, v160
	v_rsq_f32_e32 v181, v180
	s_nop 0
	v_mul_f32_e32 v181, 0xbfb8aa3b, v181
	v_mul_f32_e32 v83, v181, v83
	v_mul_f32_e32 v57, v181, v57
	v_mul_f32_e32 v61, v181, v61
	v_mul_f32_e32 v53, v181, v53
	v_mul_f32_e32 v54, v181, v54
	v_mul_f32_e32 v59, v181, v59
	v_mul_f32_e32 v63, v181, v63
	v_mul_f32_e32 v55, v181, v55
	v_exp_f32_e32 v83, v83
	v_exp_f32_e32 v57, v57
	v_exp_f32_e32 v61, v61
	v_exp_f32_e32 v53, v53
	v_exp_f32_e32 v54, v54
	v_exp_f32_e32 v59, v59
	v_exp_f32_e32 v63, v63
	v_exp_f32_e32 v55, v55
	v_fma_f32 v83, v83, v180, v180
	v_fma_f32 v57, v57, v180, v180
	v_fma_f32 v61, v61, v180, v180
	v_fma_f32 v53, v53, v180, v180
	v_fma_f32 v54, v54, v180, v180
	v_fma_f32 v59, v59, v180, v180
	v_fma_f32 v63, v63, v180, v180
	v_fma_f32 v55, v55, v180, v180
	v_rcp_f32_e32 v83, v83
	v_rcp_f32_e32 v57, v57
	v_rcp_f32_e32 v61, v61
	v_rcp_f32_e32 v53, v53
	v_rcp_f32_e32 v54, v54
	v_rcp_f32_e32 v59, v59
	v_rcp_f32_e32 v63, v63
	v_rcp_f32_e32 v55, v55
	v_mul_f32_e32 v82, v82, v83
	v_mul_f32_e32 v56, v56, v57
	v_mul_f32_e32 v60, v60, v61
	v_mul_f32_e32 v52, v52, v53
	v_mul_f32_e32 v50, v50, v54
	v_mul_f32_e32 v58, v58, v59
	v_mul_f32_e32 v62, v62, v63
	v_mul_f32_e32 v51, v51, v55
	v_cvt_pk_bf16_f32 v216, v82, v56
	v_cvt_pk_bf16_f32 v217, v60, v58
	v_cvt_pk_bf16_f32 v218, v62, v52
	v_cvt_pk_bf16_f32 v219, v50, v51
	v_mad_i64_i32 v[52:53], s[28:29], v80, s53, v[120:121]
	v_lshl_add_u64 v[52:53], v[52:53], 0, s[26:27]
	v_lshl_add_u64 v[52:53], v[52:53], 0, s[8:9]
	v_add_u32_e32 v64, 0x90, v152
	v_lshl_add_u64 v[52:53], v[52:53], 0, v[136:137]
	v_ashrrev_i32_e32 v65, 31, v64
	v_mov_b32_e32 v224, v52
	v_mov_b32_e32 v225, v53
	v_mov_b32_e32 v66, v44
	v_mov_b32_e32 v67, v40
	v_lshlrev_b64 v[48:49], 6, v[64:65]
	v_lshl_add_u64 v[60:61], s[74:75], 0, v[48:49]
	s_nop 0
	v_mov_b32_e32 v40, v45
	v_mov_b32_e32 v44, v46
	v_mov_b32_e32 v45, v42
	v_mov_b32_e32 v42, v47
	v_mov_b32_e32 v46, v32
	v_mov_b32_e32 v47, v36
	v_mov_b32_e32 v36, v33
	v_add_u32_e32 v212, 0xa0, v152
	v_ashrrev_i32_e32 v213, 31, v212
	v_lshlrev_b64 v[212:213], 6, v[212:213]
	v_lshl_add_u64 v[212:213], s[74:75], 0, v[212:213]
	global_load_dwordx4 v[180:183], v[212:213], off
	global_load_dwordx4 v[184:187], v[212:213], off offset:16
	global_load_dwordx4 v[188:191], v[212:213], off offset:32
	global_load_dwordx4 v[192:195], v[212:213], off offset:48
	global_store_dwordx4 v[224:225], v[216:219], off
	s_waitcnt vmcnt(7)
	v_pk_add_f32 v[196:197], v[196:197], v[198:199]
	v_pk_add_f32 v[200:201], v[200:201], v[202:203]
	s_waitcnt vmcnt(5)
	v_pk_add_f32 v[204:205], v[204:205], v[206:207]
	v_pk_add_f32 v[208:209], v[208:209], v[210:211]
	v_pk_add_f32 v[196:197], v[196:197], v[200:201]
	v_pk_add_f32 v[204:205], v[204:205], v[208:209]
	v_mul_f32_e32 v66, v66, v67
	v_mul_f32_e32 v40, v40, v41
	v_mul_f32_e32 v44, v44, v45
	v_mul_f32_e32 v36, v36, v37
	v_pk_add_f32 v[196:197], v[196:197], v[204:205]
	v_mul_f32_e32 v34, v34, v38
	v_mul_f32_e32 v42, v42, v43
	v_mul_f32_e32 v46, v46, v47
	v_mul_f32_e32 v35, v35, v39
	v_add_f32_e32 v196, v196, v197
	v_fmamk_f32 v196, v196, 0x3a800000, v160
	v_rsq_f32_e32 v197, v196
	s_nop 0
	v_mul_f32_e32 v197, 0xbfb8aa3b, v197
	v_mul_f32_e32 v67, v197, v67
	v_mul_f32_e32 v41, v197, v41
	v_mul_f32_e32 v45, v197, v45
	v_mul_f32_e32 v37, v197, v37
	v_mul_f32_e32 v38, v197, v38
	v_mul_f32_e32 v43, v197, v43
	v_mul_f32_e32 v47, v197, v47
	v_mul_f32_e32 v39, v197, v39
	v_exp_f32_e32 v67, v67
	v_exp_f32_e32 v41, v41
	v_exp_f32_e32 v45, v45
	v_exp_f32_e32 v37, v37
	v_exp_f32_e32 v38, v38
	v_exp_f32_e32 v43, v43
	v_exp_f32_e32 v47, v47
	v_exp_f32_e32 v39, v39
	v_fma_f32 v67, v67, v196, v196
	v_fma_f32 v41, v41, v196, v196
	v_fma_f32 v45, v45, v196, v196
	v_fma_f32 v37, v37, v196, v196
	v_fma_f32 v38, v38, v196, v196
	v_fma_f32 v43, v43, v196, v196
	v_fma_f32 v47, v47, v196, v196
	v_fma_f32 v39, v39, v196, v196
	v_rcp_f32_e32 v67, v67
	v_rcp_f32_e32 v41, v41
	v_rcp_f32_e32 v45, v45
	v_rcp_f32_e32 v37, v37
	v_rcp_f32_e32 v38, v38
	v_rcp_f32_e32 v43, v43
	v_rcp_f32_e32 v47, v47
	v_rcp_f32_e32 v39, v39
	v_mul_f32_e32 v66, v66, v67
	v_mul_f32_e32 v40, v40, v41
	v_mul_f32_e32 v44, v44, v45
	v_mul_f32_e32 v36, v36, v37
	v_mul_f32_e32 v34, v34, v38
	v_mul_f32_e32 v42, v42, v43
	v_mul_f32_e32 v46, v46, v47
	v_mul_f32_e32 v35, v35, v39
	v_cvt_pk_bf16_f32 v220, v66, v40
	v_cvt_pk_bf16_f32 v221, v44, v42
	v_cvt_pk_bf16_f32 v222, v46, v36
	v_cvt_pk_bf16_f32 v223, v34, v35
	v_mad_i64_i32 v[36:37], s[28:29], v64, s53, v[120:121]
	v_lshl_add_u64 v[36:37], v[36:37], 0, s[26:27]
	v_lshl_add_u64 v[36:37], v[36:37], 0, s[8:9]
	v_add_u32_e32 v48, 0xa0, v152
	v_lshl_add_u64 v[36:37], v[36:37], 0, v[136:137]
	v_ashrrev_i32_e32 v49, 31, v48
	v_mov_b32_e32 v226, v36
	v_mov_b32_e32 v227, v37
	v_mov_b32_e32 v50, v28
	v_mov_b32_e32 v51, v24
	v_lshlrev_b64 v[32:33], 6, v[48:49]
	v_lshl_add_u64 v[44:45], s[74:75], 0, v[32:33]
	s_nop 0
	v_mov_b32_e32 v24, v29
	v_mov_b32_e32 v28, v30
	v_mov_b32_e32 v29, v26
	v_mov_b32_e32 v26, v31
	v_mov_b32_e32 v30, v16
	v_mov_b32_e32 v31, v20
	v_mov_b32_e32 v20, v17
	v_add_u32_e32 v212, 0xb0, v152
	v_ashrrev_i32_e32 v213, 31, v212
	v_lshlrev_b64 v[212:213], 6, v[212:213]
	v_lshl_add_u64 v[212:213], s[74:75], 0, v[212:213]
	global_load_dwordx4 v[196:199], v[212:213], off
	global_load_dwordx4 v[200:203], v[212:213], off offset:16
	global_load_dwordx4 v[204:207], v[212:213], off offset:32
	global_load_dwordx4 v[208:211], v[212:213], off offset:48
	global_store_dwordx4 v[226:227], v[220:223], off
	s_waitcnt vmcnt(7)
	v_pk_add_f32 v[180:181], v[180:181], v[182:183]
	v_pk_add_f32 v[184:185], v[184:185], v[186:187]
	s_waitcnt vmcnt(5)
	v_pk_add_f32 v[188:189], v[188:189], v[190:191]
	v_pk_add_f32 v[192:193], v[192:193], v[194:195]
	v_pk_add_f32 v[180:181], v[180:181], v[184:185]
	v_pk_add_f32 v[188:189], v[188:189], v[192:193]
	v_mul_f32_e32 v50, v50, v51
	v_mul_f32_e32 v24, v24, v25
	v_mul_f32_e32 v28, v28, v29
	v_mul_f32_e32 v20, v20, v21
	v_pk_add_f32 v[180:181], v[180:181], v[188:189]
	v_mul_f32_e32 v18, v18, v22
	v_mul_f32_e32 v26, v26, v27
	v_mul_f32_e32 v30, v30, v31
	v_mul_f32_e32 v19, v19, v23
	v_add_f32_e32 v180, v180, v181
	v_fmamk_f32 v180, v180, 0x3a800000, v160
	v_rsq_f32_e32 v181, v180
	s_nop 0
	v_mul_f32_e32 v181, 0xbfb8aa3b, v181
	v_mul_f32_e32 v51, v181, v51
	v_mul_f32_e32 v25, v181, v25
	v_mul_f32_e32 v29, v181, v29
	v_mul_f32_e32 v21, v181, v21
	v_mul_f32_e32 v22, v181, v22
	v_mul_f32_e32 v27, v181, v27
	v_mul_f32_e32 v31, v181, v31
	v_mul_f32_e32 v23, v181, v23
	v_exp_f32_e32 v51, v51
	v_exp_f32_e32 v25, v25
	v_exp_f32_e32 v29, v29
	v_exp_f32_e32 v21, v21
	v_exp_f32_e32 v22, v22
	v_exp_f32_e32 v27, v27
	v_exp_f32_e32 v31, v31
	v_exp_f32_e32 v23, v23
	v_fma_f32 v51, v51, v180, v180
	v_fma_f32 v25, v25, v180, v180
	v_fma_f32 v29, v29, v180, v180
	v_fma_f32 v21, v21, v180, v180
	v_fma_f32 v22, v22, v180, v180
	v_fma_f32 v27, v27, v180, v180
	v_fma_f32 v31, v31, v180, v180
	v_fma_f32 v23, v23, v180, v180
	v_rcp_f32_e32 v51, v51
	v_rcp_f32_e32 v25, v25
	v_rcp_f32_e32 v29, v29
	v_rcp_f32_e32 v21, v21
	v_rcp_f32_e32 v22, v22
	v_rcp_f32_e32 v27, v27
	v_rcp_f32_e32 v31, v31
	v_rcp_f32_e32 v23, v23
	v_mul_f32_e32 v50, v50, v51
	v_mul_f32_e32 v24, v24, v25
	v_mul_f32_e32 v28, v28, v29
	v_mul_f32_e32 v20, v20, v21
	v_mul_f32_e32 v18, v18, v22
	v_mul_f32_e32 v26, v26, v27
	v_mul_f32_e32 v30, v30, v31
	v_mul_f32_e32 v19, v19, v23
	v_cvt_pk_bf16_f32 v216, v50, v24
	v_cvt_pk_bf16_f32 v217, v28, v26
	v_cvt_pk_bf16_f32 v218, v30, v20
	v_cvt_pk_bf16_f32 v219, v18, v19
	v_mad_i64_i32 v[20:21], s[28:29], v48, s53, v[120:121]
	v_lshl_add_u64 v[20:21], v[20:21], 0, s[26:27]
	v_lshl_add_u64 v[20:21], v[20:21], 0, s[8:9]
	v_add_u32_e32 v32, 0xb0, v152
	v_lshl_add_u64 v[20:21], v[20:21], 0, v[136:137]
	v_ashrrev_i32_e32 v33, 31, v32
	v_mov_b32_e32 v224, v20
	v_mov_b32_e32 v225, v21
	v_mov_b32_e32 v34, v12
	v_mov_b32_e32 v35, v8
	v_lshlrev_b64 v[16:17], 6, v[32:33]
	v_lshl_add_u64 v[28:29], s[74:75], 0, v[16:17]
	s_nop 0
	v_mov_b32_e32 v8, v13
	v_mov_b32_e32 v12, v14
	v_mov_b32_e32 v13, v10
	v_mov_b32_e32 v10, v15
	v_mov_b32_e32 v14, v0
	v_mov_b32_e32 v15, v4
	v_mov_b32_e32 v4, v1
	global_store_dwordx4 v[224:225], v[216:219], off
	s_waitcnt vmcnt(3)
	v_pk_add_f32 v[196:197], v[196:197], v[198:199]
	v_pk_add_f32 v[200:201], v[200:201], v[202:203]
	s_waitcnt vmcnt(1)
	v_pk_add_f32 v[204:205], v[204:205], v[206:207]
	v_pk_add_f32 v[208:209], v[208:209], v[210:211]
	v_pk_add_f32 v[196:197], v[196:197], v[200:201]
	v_pk_add_f32 v[204:205], v[204:205], v[208:209]
	v_mul_f32_e32 v34, v34, v35
	v_mul_f32_e32 v8, v8, v9
	v_mul_f32_e32 v12, v12, v13
	v_mul_f32_e32 v4, v4, v5
	v_pk_add_f32 v[196:197], v[196:197], v[204:205]
	v_mul_f32_e32 v2, v2, v6
	v_mul_f32_e32 v10, v10, v11
	v_mul_f32_e32 v14, v14, v15
	v_mul_f32_e32 v3, v3, v7
	v_add_f32_e32 v196, v196, v197
	v_fmamk_f32 v196, v196, 0x3a800000, v160
	v_rsq_f32_e32 v197, v196
	s_nop 0
	v_mul_f32_e32 v197, 0xbfb8aa3b, v197
	v_mul_f32_e32 v35, v197, v35
	v_mul_f32_e32 v9, v197, v9
	v_mul_f32_e32 v13, v197, v13
	v_mul_f32_e32 v5, v197, v5
	v_mul_f32_e32 v6, v197, v6
	v_mul_f32_e32 v11, v197, v11
	v_mul_f32_e32 v15, v197, v15
	v_mul_f32_e32 v7, v197, v7
	v_exp_f32_e32 v35, v35
	v_exp_f32_e32 v9, v9
	v_exp_f32_e32 v13, v13
	v_exp_f32_e32 v5, v5
	v_exp_f32_e32 v6, v6
	v_exp_f32_e32 v11, v11
	v_exp_f32_e32 v15, v15
	v_exp_f32_e32 v7, v7
	v_fma_f32 v35, v35, v196, v196
	v_fma_f32 v9, v9, v196, v196
	v_fma_f32 v13, v13, v196, v196
	v_fma_f32 v5, v5, v196, v196
	v_fma_f32 v6, v6, v196, v196
	v_fma_f32 v11, v11, v196, v196
	v_fma_f32 v15, v15, v196, v196
	v_fma_f32 v7, v7, v196, v196
	v_rcp_f32_e32 v35, v35
	v_rcp_f32_e32 v9, v9
	v_rcp_f32_e32 v13, v13
	v_rcp_f32_e32 v5, v5
	v_rcp_f32_e32 v6, v6
	v_rcp_f32_e32 v11, v11
	v_rcp_f32_e32 v15, v15
	v_rcp_f32_e32 v7, v7
	v_mul_f32_e32 v34, v34, v35
	v_mul_f32_e32 v8, v8, v9
	v_mul_f32_e32 v12, v12, v13
	v_mul_f32_e32 v4, v4, v5
	v_mul_f32_e32 v2, v2, v6
	v_mul_f32_e32 v10, v10, v11
	v_mul_f32_e32 v14, v14, v15
	v_mul_f32_e32 v3, v3, v7
	v_cvt_pk_bf16_f32 v220, v34, v8
	v_cvt_pk_bf16_f32 v221, v12, v10
	v_cvt_pk_bf16_f32 v222, v14, v4
	v_cvt_pk_bf16_f32 v223, v2, v3
	v_mad_i64_i32 v[4:5], s[28:29], v32, s53, v[120:121]
	v_lshl_add_u64 v[4:5], v[4:5], 0, s[26:27]
	v_lshl_add_u64 v[4:5], v[4:5], 0, s[8:9]
	v_lshl_add_u64 v[4:5], v[4:5], 0, v[136:137]
	global_store_dwordx4 v[4:5], v[220:223], off
	s_nop 1
	s_andn2_b64 vcc, exec, s[4:5]
	s_mov_b64 s[4:5], -1
	s_cbranch_vccnz .LBB0_973
	s_branch .LBB0_1007

.LBB0_1135:
	v_ashrrev_i32_e32 v155, 31, v154
	v_lshlrev_b64 v[156:157], 6, v[154:155]
	v_lshl_add_u64 v[156:157], s[74:75], 0, v[156:157]
	v_mov_b32_e32 v156, v124
	v_mov_b32_e32 v157, v116
	v_mov_b32_e32 v116, v125
	v_mov_b32_e32 v124, v126
	v_mov_b32_e32 v125, v118
	v_mov_b32_e32 v118, v127
	v_mov_b32_e32 v126, v120
	v_mov_b32_e32 v127, v112
	v_mov_b32_e32 v112, v121
	v_mov_b32_e32 v182, v122
	v_mov_b32_e32 v183, v114
	v_mov_b32_e32 v114, v123
	s_lshl_b32 s28, s28, 7
	v_mov_b64_e32 v[120:121], s[72:73]
	s_ashr_i32 s29, s28, 31
	v_mad_i64_i32 v[122:123], s[30:31], v154, s54, v[120:121]
	s_lshl_b64 s[28:29], s[28:29], 1
	v_lshl_add_u64 v[122:123], v[122:123], 0, s[28:29]
	v_lshl_add_u64 v[122:123], v[122:123], 0, s[8:9]
	v_mov_b32_e32 v220, v154
	v_ashrrev_i32_e32 v221, 31, v220
	v_lshlrev_b64 v[220:221], 6, v[220:221]
	v_lshl_add_u64 v[220:221], s[74:75], 0, v[220:221]
	global_load_dwordx4 v[188:191], v[220:221], off
	global_load_dwordx4 v[192:195], v[220:221], off offset:16
	global_load_dwordx4 v[196:199], v[220:221], off offset:32
	global_load_dwordx4 v[200:203], v[220:221], off offset:48
	v_or_b32_e32 v220, 16, v154
	v_ashrrev_i32_e32 v221, 31, v220
	v_lshlrev_b64 v[220:221], 6, v[220:221]
	v_lshl_add_u64 v[220:221], s[74:75], 0, v[220:221]
	global_load_dwordx4 v[204:207], v[220:221], off
	global_load_dwordx4 v[208:211], v[220:221], off offset:16
	global_load_dwordx4 v[212:215], v[220:221], off offset:32
	global_load_dwordx4 v[216:219], v[220:221], off offset:48
	s_waitcnt vmcnt(6)
	v_pk_add_f32 v[188:189], v[188:189], v[190:191]
	v_pk_add_f32 v[192:193], v[192:193], v[194:195]
	s_waitcnt vmcnt(4)
	v_pk_add_f32 v[196:197], v[196:197], v[198:199]
	v_pk_add_f32 v[200:201], v[200:201], v[202:203]
	v_pk_add_f32 v[188:189], v[188:189], v[192:193]
	v_pk_add_f32 v[196:197], v[196:197], v[200:201]
	v_mul_f32_e32 v116, v116, v117
	v_mul_f32_e32 v124, v124, v125
	v_mul_f32_e32 v118, v118, v119
	v_mul_f32_e32 v126, v126, v127
	v_pk_add_f32 v[188:189], v[188:189], v[196:197]
	v_mul_f32_e32 v156, v156, v157
	v_mul_f32_e32 v112, v112, v113
	v_mul_f32_e32 v182, v182, v183
	v_mul_f32_e32 v114, v114, v115
	v_add_f32_e32 v188, v188, v189
	v_fmamk_f32 v188, v188, 0x3a800000, v163
	v_rsq_f32_e32 v189, v188
	s_nop 0
	v_mul_f32_e32 v189, 0xbfb8aa3b, v189
	v_mul_f32_e32 v117, v189, v117
	v_mul_f32_e32 v125, v189, v125
	v_mul_f32_e32 v119, v189, v119
	v_mul_f32_e32 v127, v189, v127
	v_mul_f32_e32 v157, v189, v157
	v_mul_f32_e32 v113, v189, v113
	v_mul_f32_e32 v183, v189, v183
	v_mul_f32_e32 v115, v189, v115
	v_exp_f32_e32 v117, v117
	v_exp_f32_e32 v125, v125
	v_exp_f32_e32 v119, v119
	v_exp_f32_e32 v127, v127
	v_exp_f32_e32 v157, v157
	v_exp_f32_e32 v113, v113
	v_exp_f32_e32 v183, v183
	v_exp_f32_e32 v115, v115
	v_fma_f32 v117, v117, v188, v188
	v_fma_f32 v125, v125, v188, v188
	v_fma_f32 v119, v119, v188, v188
	v_fma_f32 v127, v127, v188, v188
	v_fma_f32 v157, v157, v188, v188
	v_fma_f32 v113, v113, v188, v188
	v_fma_f32 v183, v183, v188, v188
	v_fma_f32 v115, v115, v188, v188
	v_rcp_f32_e32 v117, v117
	v_rcp_f32_e32 v125, v125
	v_rcp_f32_e32 v119, v119
	v_rcp_f32_e32 v127, v127
	v_rcp_f32_e32 v157, v157
	v_rcp_f32_e32 v113, v113
	v_rcp_f32_e32 v183, v183
	v_rcp_f32_e32 v115, v115
	v_mul_f32_e32 v116, v116, v117
	v_mul_f32_e32 v124, v124, v125
	v_mul_f32_e32 v118, v118, v119
	v_mul_f32_e32 v126, v126, v127
	v_mul_f32_e32 v156, v156, v157
	v_mul_f32_e32 v112, v112, v113
	v_mul_f32_e32 v182, v182, v183
	v_mul_f32_e32 v114, v114, v115
	v_cvt_pk_bf16_f32 v224, v156, v116
	v_cvt_pk_bf16_f32 v225, v124, v118
	v_cvt_pk_bf16_f32 v226, v126, v112
	v_cvt_pk_bf16_f32 v227, v182, v114
	v_or_b32_e32 v126, 16, v154
	v_lshl_add_u64 v[116:117], v[122:123], 0, v[136:137]
	v_ashrrev_i32_e32 v127, 31, v126
	v_mov_b32_e32 v232, v116
	v_mov_b32_e32 v233, v117
	s_nop 1
	v_lshlrev_b64 v[112:113], 6, v[126:127]
	v_lshl_add_u64 v[156:157], s[74:75], 0, v[112:113]
	v_mov_b32_e32 v156, v108
	v_mov_b32_e32 v157, v100
	v_mov_b32_e32 v100, v109
	v_mov_b32_e32 v108, v110
	v_mov_b32_e32 v109, v102
	v_mov_b32_e32 v102, v111
	v_mov_b32_e32 v110, v104
	v_mov_b32_e32 v111, v96
	v_mov_b32_e32 v96, v105
	v_mov_b32_e32 v104, v106
	v_mov_b32_e32 v105, v98
	v_mov_b32_e32 v98, v107
	v_or_b32_e32 v220, 32, v154
	v_ashrrev_i32_e32 v221, 31, v220
	v_lshlrev_b64 v[220:221], 6, v[220:221]
	v_lshl_add_u64 v[220:221], s[74:75], 0, v[220:221]
	global_load_dwordx4 v[188:191], v[220:221], off
	global_load_dwordx4 v[192:195], v[220:221], off offset:16
	global_load_dwordx4 v[196:199], v[220:221], off offset:32
	global_load_dwordx4 v[200:203], v[220:221], off offset:48
	global_store_dwordx4 v[232:233], v[224:227], off
	s_waitcnt vmcnt(7)
	v_pk_add_f32 v[204:205], v[204:205], v[206:207]
	v_pk_add_f32 v[208:209], v[208:209], v[210:211]
	s_waitcnt vmcnt(5)
	v_pk_add_f32 v[212:213], v[212:213], v[214:215]
	v_pk_add_f32 v[216:217], v[216:217], v[218:219]
	v_pk_add_f32 v[204:205], v[204:205], v[208:209]
	v_pk_add_f32 v[212:213], v[212:213], v[216:217]
	v_mul_f32_e32 v100, v100, v101
	v_mul_f32_e32 v108, v108, v109
	v_mul_f32_e32 v156, v156, v157
	v_mul_f32_e32 v102, v102, v103
	v_pk_add_f32 v[204:205], v[204:205], v[212:213]
	v_mul_f32_e32 v110, v110, v111
	v_mul_f32_e32 v96, v96, v97
	v_mul_f32_e32 v104, v104, v105
	v_mul_f32_e32 v98, v98, v99
	v_add_f32_e32 v204, v204, v205
	v_fmamk_f32 v204, v204, 0x3a800000, v163
	v_rsq_f32_e32 v205, v204
	s_nop 0
	v_mul_f32_e32 v205, 0xbfb8aa3b, v205
	v_mul_f32_e32 v101, v205, v101
	v_mul_f32_e32 v109, v205, v109
	v_mul_f32_e32 v157, v205, v157
	v_mul_f32_e32 v103, v205, v103
	v_mul_f32_e32 v111, v205, v111
	v_mul_f32_e32 v97, v205, v97
	v_mul_f32_e32 v105, v205, v105
	v_mul_f32_e32 v99, v205, v99
	v_exp_f32_e32 v101, v101
	v_exp_f32_e32 v109, v109
	v_exp_f32_e32 v157, v157
	v_exp_f32_e32 v103, v103
	v_exp_f32_e32 v111, v111
	v_exp_f32_e32 v97, v97
	v_exp_f32_e32 v105, v105
	v_exp_f32_e32 v99, v99
	v_fma_f32 v101, v101, v204, v204
	v_fma_f32 v109, v109, v204, v204
	v_fma_f32 v157, v157, v204, v204
	v_fma_f32 v103, v103, v204, v204
	v_fma_f32 v111, v111, v204, v204
	v_fma_f32 v97, v97, v204, v204
	v_fma_f32 v105, v105, v204, v204
	v_fma_f32 v99, v99, v204, v204
	v_rcp_f32_e32 v101, v101
	v_rcp_f32_e32 v109, v109
	v_rcp_f32_e32 v157, v157
	v_rcp_f32_e32 v103, v103
	v_rcp_f32_e32 v111, v111
	v_rcp_f32_e32 v97, v97
	v_rcp_f32_e32 v105, v105
	v_rcp_f32_e32 v99, v99
	v_mul_f32_e32 v100, v100, v101
	v_mul_f32_e32 v108, v108, v109
	v_mul_f32_e32 v156, v156, v157
	v_mul_f32_e32 v102, v102, v103
	v_mul_f32_e32 v110, v110, v111
	v_mul_f32_e32 v96, v96, v97
	v_mul_f32_e32 v104, v104, v105
	v_mul_f32_e32 v98, v98, v99
	v_cvt_pk_bf16_f32 v228, v156, v100
	v_cvt_pk_bf16_f32 v229, v108, v102
	v_cvt_pk_bf16_f32 v230, v110, v96
	v_cvt_pk_bf16_f32 v231, v104, v98
	v_mad_i64_i32 v[112:113], s[30:31], v126, s54, v[120:121]
	v_lshl_add_u64 v[112:113], v[112:113], 0, s[28:29]
	v_lshl_add_u64 v[100:101], v[112:113], 0, s[8:9]
	v_or_b32_e32 v112, 32, v154
	v_lshl_add_u64 v[100:101], v[100:101], 0, v[136:137]
	v_ashrrev_i32_e32 v113, 31, v112
	v_mov_b32_e32 v234, v100
	v_mov_b32_e32 v235, v101
	v_mov_b32_e32 v114, v92
	v_mov_b32_e32 v92, v94
	v_lshlrev_b64 v[96:97], 6, v[112:113]
	v_lshl_add_u64 v[108:109], s[74:75], 0, v[96:97]
	s_nop 0
	v_mov_b32_e32 v94, v80
	v_mov_b32_e32 v80, v82
	v_mov_b32_e32 v115, v88
	v_mov_b32_e32 v88, v93
	v_mov_b32_e32 v93, v90
	v_mov_b32_e32 v90, v95
	v_mov_b32_e32 v95, v84
	v_mov_b32_e32 v84, v81
	v_mov_b32_e32 v81, v86
	v_mov_b32_e32 v86, v83
	v_or_b32_e32 v220, 48, v154
	v_ashrrev_i32_e32 v221, 31, v220
	v_lshlrev_b64 v[220:221], 6, v[220:221]
	v_lshl_add_u64 v[220:221], s[74:75], 0, v[220:221]
	global_load_dwordx4 v[204:207], v[220:221], off
	global_load_dwordx4 v[208:211], v[220:221], off offset:16
	global_load_dwordx4 v[212:215], v[220:221], off offset:32
	global_load_dwordx4 v[216:219], v[220:221], off offset:48
	global_store_dwordx4 v[234:235], v[228:231], off
	s_waitcnt vmcnt(7)
	v_pk_add_f32 v[188:189], v[188:189], v[190:191]
	v_pk_add_f32 v[192:193], v[192:193], v[194:195]
	s_waitcnt vmcnt(5)
	v_pk_add_f32 v[196:197], v[196:197], v[198:199]
	v_pk_add_f32 v[200:201], v[200:201], v[202:203]
	v_pk_add_f32 v[188:189], v[188:189], v[192:193]
	v_pk_add_f32 v[196:197], v[196:197], v[200:201]
	v_mul_f32_e32 v114, v114, v115
	v_mul_f32_e32 v88, v88, v89
	v_mul_f32_e32 v92, v92, v93
	v_mul_f32_e32 v90, v90, v91
	v_pk_add_f32 v[188:189], v[188:189], v[196:197]
	v_mul_f32_e32 v94, v94, v95
	v_mul_f32_e32 v84, v84, v85
	v_mul_f32_e32 v80, v80, v81
	v_mul_f32_e32 v86, v86, v87
	v_add_f32_e32 v188, v188, v189
	v_fmamk_f32 v188, v188, 0x3a800000, v163
	v_rsq_f32_e32 v189, v188
	s_nop 0
	v_mul_f32_e32 v189, 0xbfb8aa3b, v189
	v_mul_f32_e32 v115, v189, v115
	v_mul_f32_e32 v89, v189, v89
	v_mul_f32_e32 v93, v189, v93
	v_mul_f32_e32 v91, v189, v91
	v_mul_f32_e32 v95, v189, v95
	v_mul_f32_e32 v85, v189, v85
	v_mul_f32_e32 v81, v189, v81
	v_mul_f32_e32 v87, v189, v87
	v_exp_f32_e32 v115, v115
	v_exp_f32_e32 v89, v89
	v_exp_f32_e32 v93, v93
	v_exp_f32_e32 v91, v91
	v_exp_f32_e32 v95, v95
	v_exp_f32_e32 v85, v85
	v_exp_f32_e32 v81, v81
	v_exp_f32_e32 v87, v87
	v_fma_f32 v115, v115, v188, v188
	v_fma_f32 v89, v89, v188, v188
	v_fma_f32 v93, v93, v188, v188
	v_fma_f32 v91, v91, v188, v188
	v_fma_f32 v95, v95, v188, v188
	v_fma_f32 v85, v85, v188, v188
	v_fma_f32 v81, v81, v188, v188
	v_fma_f32 v87, v87, v188, v188
	v_rcp_f32_e32 v115, v115
	v_rcp_f32_e32 v89, v89
	v_rcp_f32_e32 v93, v93
	v_rcp_f32_e32 v91, v91
	v_rcp_f32_e32 v95, v95
	v_rcp_f32_e32 v85, v85
	v_rcp_f32_e32 v81, v81
	v_rcp_f32_e32 v87, v87
	v_mul_f32_e32 v114, v114, v115
	v_mul_f32_e32 v88, v88, v89
	v_mul_f32_e32 v92, v92, v93
	v_mul_f32_e32 v90, v90, v91
	v_mul_f32_e32 v94, v94, v95
	v_mul_f32_e32 v84, v84, v85
	v_mul_f32_e32 v80, v80, v81
	v_mul_f32_e32 v86, v86, v87
	v_cvt_pk_bf16_f32 v224, v114, v88
	v_cvt_pk_bf16_f32 v225, v92, v90
	v_cvt_pk_bf16_f32 v226, v94, v84
	v_cvt_pk_bf16_f32 v227, v80, v86
	v_mad_i64_i32 v[96:97], s[30:31], v112, s54, v[120:121]
	v_lshl_add_u64 v[84:85], v[96:97], 0, s[28:29]
	v_lshl_add_u64 v[84:85], v[84:85], 0, s[8:9]
	v_or_b32_e32 v96, 48, v154
	v_lshl_add_u64 v[84:85], v[84:85], 0, v[136:137]
	v_ashrrev_i32_e32 v97, 31, v96
	v_mov_b32_e32 v232, v84
	v_mov_b32_e32 v233, v85
	v_mov_b32_e32 v98, v76
	v_mov_b32_e32 v99, v72
	v_lshlrev_b64 v[80:81], 6, v[96:97]
	v_lshl_add_u64 v[92:93], s[74:75], 0, v[80:81]
	s_nop 0
	v_mov_b32_e32 v72, v77
	v_mov_b32_e32 v76, v78
	v_mov_b32_e32 v77, v74
	v_mov_b32_e32 v74, v79
	v_mov_b32_e32 v78, v64
	v_mov_b32_e32 v79, v68
	v_mov_b32_e32 v68, v65
	v_add_u32_e32 v220, 0x80, v154
	v_ashrrev_i32_e32 v221, 31, v220
	v_lshlrev_b64 v[220:221], 6, v[220:221]
	v_lshl_add_u64 v[220:221], s[74:75], 0, v[220:221]
	global_load_dwordx4 v[188:191], v[220:221], off
	global_load_dwordx4 v[192:195], v[220:221], off offset:16
	global_load_dwordx4 v[196:199], v[220:221], off offset:32
	global_load_dwordx4 v[200:203], v[220:221], off offset:48
	global_store_dwordx4 v[232:233], v[224:227], off
	s_waitcnt vmcnt(7)
	v_pk_add_f32 v[204:205], v[204:205], v[206:207]
	v_pk_add_f32 v[208:209], v[208:209], v[210:211]
	s_waitcnt vmcnt(5)
	v_pk_add_f32 v[212:213], v[212:213], v[214:215]
	v_pk_add_f32 v[216:217], v[216:217], v[218:219]
	v_pk_add_f32 v[204:205], v[204:205], v[208:209]
	v_pk_add_f32 v[212:213], v[212:213], v[216:217]
	v_mul_f32_e32 v98, v98, v99
	v_mul_f32_e32 v72, v72, v73
	v_mul_f32_e32 v76, v76, v77
	v_mul_f32_e32 v68, v68, v69
	v_pk_add_f32 v[204:205], v[204:205], v[212:213]
	v_mul_f32_e32 v66, v66, v70
	v_mul_f32_e32 v74, v74, v75
	v_mul_f32_e32 v78, v78, v79
	v_mul_f32_e32 v67, v67, v71
	v_add_f32_e32 v204, v204, v205
	v_fmamk_f32 v204, v204, 0x3a800000, v163
	v_rsq_f32_e32 v205, v204
	s_nop 0
	v_mul_f32_e32 v205, 0xbfb8aa3b, v205
	v_mul_f32_e32 v99, v205, v99
	v_mul_f32_e32 v73, v205, v73
	v_mul_f32_e32 v77, v205, v77
	v_mul_f32_e32 v69, v205, v69
	v_mul_f32_e32 v70, v205, v70
	v_mul_f32_e32 v75, v205, v75
	v_mul_f32_e32 v79, v205, v79
	v_mul_f32_e32 v71, v205, v71
	v_exp_f32_e32 v99, v99
	v_exp_f32_e32 v73, v73
	v_exp_f32_e32 v77, v77
	v_exp_f32_e32 v69, v69
	v_exp_f32_e32 v70, v70
	v_exp_f32_e32 v75, v75
	v_exp_f32_e32 v79, v79
	v_exp_f32_e32 v71, v71
	v_fma_f32 v99, v99, v204, v204
	v_fma_f32 v73, v73, v204, v204
	v_fma_f32 v77, v77, v204, v204
	v_fma_f32 v69, v69, v204, v204
	v_fma_f32 v70, v70, v204, v204
	v_fma_f32 v75, v75, v204, v204
	v_fma_f32 v79, v79, v204, v204
	v_fma_f32 v71, v71, v204, v204
	v_rcp_f32_e32 v99, v99
	v_rcp_f32_e32 v73, v73
	v_rcp_f32_e32 v77, v77
	v_rcp_f32_e32 v69, v69
	v_rcp_f32_e32 v70, v70
	v_rcp_f32_e32 v75, v75
	v_rcp_f32_e32 v79, v79
	v_rcp_f32_e32 v71, v71
	v_mul_f32_e32 v98, v98, v99
	v_mul_f32_e32 v72, v72, v73
	v_mul_f32_e32 v76, v76, v77
	v_mul_f32_e32 v68, v68, v69
	v_mul_f32_e32 v66, v66, v70
	v_mul_f32_e32 v74, v74, v75
	v_mul_f32_e32 v78, v78, v79
	v_mul_f32_e32 v67, v67, v71
	v_cvt_pk_bf16_f32 v228, v98, v72
	v_cvt_pk_bf16_f32 v229, v76, v74
	v_cvt_pk_bf16_f32 v230, v78, v68
	v_cvt_pk_bf16_f32 v231, v66, v67
	v_mad_i64_i32 v[68:69], s[30:31], v96, s54, v[120:121]
	v_lshl_add_u64 v[68:69], v[68:69], 0, s[28:29]
	v_lshl_add_u64 v[68:69], v[68:69], 0, s[8:9]
	v_add_u32_e32 v80, 0x80, v154
	v_lshl_add_u64 v[68:69], v[68:69], 0, v[136:137]
	v_ashrrev_i32_e32 v81, 31, v80
	v_mov_b32_e32 v234, v68
	v_mov_b32_e32 v235, v69
	v_mov_b32_e32 v82, v60
	v_mov_b32_e32 v83, v56
	v_lshlrev_b64 v[64:65], 6, v[80:81]
	v_lshl_add_u64 v[76:77], s[74:75], 0, v[64:65]
	s_nop 0
	v_mov_b32_e32 v56, v61
	v_mov_b32_e32 v60, v62
	v_mov_b32_e32 v61, v58
	v_mov_b32_e32 v58, v63
	v_mov_b32_e32 v62, v48
	v_mov_b32_e32 v63, v52
	v_mov_b32_e32 v52, v49
	v_add_u32_e32 v220, 0x90, v154
	v_ashrrev_i32_e32 v221, 31, v220
	v_lshlrev_b64 v[220:221], 6, v[220:221]
	v_lshl_add_u64 v[220:221], s[74:75], 0, v[220:221]
	global_load_dwordx4 v[204:207], v[220:221], off
	global_load_dwordx4 v[208:211], v[220:221], off offset:16
	global_load_dwordx4 v[212:215], v[220:221], off offset:32
	global_load_dwordx4 v[216:219], v[220:221], off offset:48
	global_store_dwordx4 v[234:235], v[228:231], off
	s_waitcnt vmcnt(7)
	v_pk_add_f32 v[188:189], v[188:189], v[190:191]
	v_pk_add_f32 v[192:193], v[192:193], v[194:195]
	s_waitcnt vmcnt(5)
	v_pk_add_f32 v[196:197], v[196:197], v[198:199]
	v_pk_add_f32 v[200:201], v[200:201], v[202:203]
	v_pk_add_f32 v[188:189], v[188:189], v[192:193]
	v_pk_add_f32 v[196:197], v[196:197], v[200:201]
	v_mul_f32_e32 v82, v82, v83
	v_mul_f32_e32 v56, v56, v57
	v_mul_f32_e32 v60, v60, v61
	v_mul_f32_e32 v52, v52, v53
	v_pk_add_f32 v[188:189], v[188:189], v[196:197]
	v_mul_f32_e32 v50, v50, v54
	v_mul_f32_e32 v58, v58, v59
	v_mul_f32_e32 v62, v62, v63
	v_mul_f32_e32 v51, v51, v55
	v_add_f32_e32 v188, v188, v189
	v_fmamk_f32 v188, v188, 0x3a800000, v163
	v_rsq_f32_e32 v189, v188
	s_nop 0
	v_mul_f32_e32 v189, 0xbfb8aa3b, v189
	v_mul_f32_e32 v83, v189, v83
	v_mul_f32_e32 v57, v189, v57
	v_mul_f32_e32 v61, v189, v61
	v_mul_f32_e32 v53, v189, v53
	v_mul_f32_e32 v54, v189, v54
	v_mul_f32_e32 v59, v189, v59
	v_mul_f32_e32 v63, v189, v63
	v_mul_f32_e32 v55, v189, v55
	v_exp_f32_e32 v83, v83
	v_exp_f32_e32 v57, v57
	v_exp_f32_e32 v61, v61
	v_exp_f32_e32 v53, v53
	v_exp_f32_e32 v54, v54
	v_exp_f32_e32 v59, v59
	v_exp_f32_e32 v63, v63
	v_exp_f32_e32 v55, v55
	v_fma_f32 v83, v83, v188, v188
	v_fma_f32 v57, v57, v188, v188
	v_fma_f32 v61, v61, v188, v188
	v_fma_f32 v53, v53, v188, v188
	v_fma_f32 v54, v54, v188, v188
	v_fma_f32 v59, v59, v188, v188
	v_fma_f32 v63, v63, v188, v188
	v_fma_f32 v55, v55, v188, v188
	v_rcp_f32_e32 v83, v83
	v_rcp_f32_e32 v57, v57
	v_rcp_f32_e32 v61, v61
	v_rcp_f32_e32 v53, v53
	v_rcp_f32_e32 v54, v54
	v_rcp_f32_e32 v59, v59
	v_rcp_f32_e32 v63, v63
	v_rcp_f32_e32 v55, v55
	v_mul_f32_e32 v82, v82, v83
	v_mul_f32_e32 v56, v56, v57
	v_mul_f32_e32 v60, v60, v61
	v_mul_f32_e32 v52, v52, v53
	v_mul_f32_e32 v50, v50, v54
	v_mul_f32_e32 v58, v58, v59
	v_mul_f32_e32 v62, v62, v63
	v_mul_f32_e32 v51, v51, v55
	v_cvt_pk_bf16_f32 v224, v82, v56
	v_cvt_pk_bf16_f32 v225, v60, v58
	v_cvt_pk_bf16_f32 v226, v62, v52
	v_cvt_pk_bf16_f32 v227, v50, v51
	v_mad_i64_i32 v[52:53], s[30:31], v80, s54, v[120:121]
	v_lshl_add_u64 v[52:53], v[52:53], 0, s[28:29]
	v_lshl_add_u64 v[52:53], v[52:53], 0, s[8:9]
	v_add_u32_e32 v64, 0x90, v154
	v_lshl_add_u64 v[52:53], v[52:53], 0, v[136:137]
	v_ashrrev_i32_e32 v65, 31, v64
	v_mov_b32_e32 v232, v52
	v_mov_b32_e32 v233, v53
	v_mov_b32_e32 v66, v44
	v_mov_b32_e32 v67, v40
	v_lshlrev_b64 v[48:49], 6, v[64:65]
	v_lshl_add_u64 v[60:61], s[74:75], 0, v[48:49]
	s_nop 0
	v_mov_b32_e32 v40, v45
	v_mov_b32_e32 v44, v46
	v_mov_b32_e32 v45, v42
	v_mov_b32_e32 v42, v47
	v_mov_b32_e32 v46, v32
	v_mov_b32_e32 v47, v36
	v_mov_b32_e32 v36, v33
	v_add_u32_e32 v220, 0xa0, v154
	v_ashrrev_i32_e32 v221, 31, v220
	v_lshlrev_b64 v[220:221], 6, v[220:221]
	v_lshl_add_u64 v[220:221], s[74:75], 0, v[220:221]
	global_load_dwordx4 v[188:191], v[220:221], off
	global_load_dwordx4 v[192:195], v[220:221], off offset:16
	global_load_dwordx4 v[196:199], v[220:221], off offset:32
	global_load_dwordx4 v[200:203], v[220:221], off offset:48
	global_store_dwordx4 v[232:233], v[224:227], off
	s_waitcnt vmcnt(7)
	v_pk_add_f32 v[204:205], v[204:205], v[206:207]
	v_pk_add_f32 v[208:209], v[208:209], v[210:211]
	s_waitcnt vmcnt(5)
	v_pk_add_f32 v[212:213], v[212:213], v[214:215]
	v_pk_add_f32 v[216:217], v[216:217], v[218:219]
	v_pk_add_f32 v[204:205], v[204:205], v[208:209]
	v_pk_add_f32 v[212:213], v[212:213], v[216:217]
	v_mul_f32_e32 v66, v66, v67
	v_mul_f32_e32 v40, v40, v41
	v_mul_f32_e32 v44, v44, v45
	v_mul_f32_e32 v36, v36, v37
	v_pk_add_f32 v[204:205], v[204:205], v[212:213]
	v_mul_f32_e32 v34, v34, v38
	v_mul_f32_e32 v42, v42, v43
	v_mul_f32_e32 v46, v46, v47
	v_mul_f32_e32 v35, v35, v39
	v_add_f32_e32 v204, v204, v205
	v_fmamk_f32 v204, v204, 0x3a800000, v163
	v_rsq_f32_e32 v205, v204
	s_nop 0
	v_mul_f32_e32 v205, 0xbfb8aa3b, v205
	v_mul_f32_e32 v67, v205, v67
	v_mul_f32_e32 v41, v205, v41
	v_mul_f32_e32 v45, v205, v45
	v_mul_f32_e32 v37, v205, v37
	v_mul_f32_e32 v38, v205, v38
	v_mul_f32_e32 v43, v205, v43
	v_mul_f32_e32 v47, v205, v47
	v_mul_f32_e32 v39, v205, v39
	v_exp_f32_e32 v67, v67
	v_exp_f32_e32 v41, v41
	v_exp_f32_e32 v45, v45
	v_exp_f32_e32 v37, v37
	v_exp_f32_e32 v38, v38
	v_exp_f32_e32 v43, v43
	v_exp_f32_e32 v47, v47
	v_exp_f32_e32 v39, v39
	v_fma_f32 v67, v67, v204, v204
	v_fma_f32 v41, v41, v204, v204
	v_fma_f32 v45, v45, v204, v204
	v_fma_f32 v37, v37, v204, v204
	v_fma_f32 v38, v38, v204, v204
	v_fma_f32 v43, v43, v204, v204
	v_fma_f32 v47, v47, v204, v204
	v_fma_f32 v39, v39, v204, v204
	v_rcp_f32_e32 v67, v67
	v_rcp_f32_e32 v41, v41
	v_rcp_f32_e32 v45, v45
	v_rcp_f32_e32 v37, v37
	v_rcp_f32_e32 v38, v38
	v_rcp_f32_e32 v43, v43
	v_rcp_f32_e32 v47, v47
	v_rcp_f32_e32 v39, v39
	v_mul_f32_e32 v66, v66, v67
	v_mul_f32_e32 v40, v40, v41
	v_mul_f32_e32 v44, v44, v45
	v_mul_f32_e32 v36, v36, v37
	v_mul_f32_e32 v34, v34, v38
	v_mul_f32_e32 v42, v42, v43
	v_mul_f32_e32 v46, v46, v47
	v_mul_f32_e32 v35, v35, v39
	v_cvt_pk_bf16_f32 v228, v66, v40
	v_cvt_pk_bf16_f32 v229, v44, v42
	v_cvt_pk_bf16_f32 v230, v46, v36
	v_cvt_pk_bf16_f32 v231, v34, v35
	v_mad_i64_i32 v[36:37], s[30:31], v64, s54, v[120:121]
	v_lshl_add_u64 v[36:37], v[36:37], 0, s[28:29]
	v_lshl_add_u64 v[36:37], v[36:37], 0, s[8:9]
	v_add_u32_e32 v48, 0xa0, v154
	v_lshl_add_u64 v[36:37], v[36:37], 0, v[136:137]
	v_ashrrev_i32_e32 v49, 31, v48
	v_mov_b32_e32 v234, v36
	v_mov_b32_e32 v235, v37
	v_mov_b32_e32 v50, v28
	v_mov_b32_e32 v51, v24
	v_lshlrev_b64 v[32:33], 6, v[48:49]
	v_lshl_add_u64 v[44:45], s[74:75], 0, v[32:33]
	s_nop 0
	v_mov_b32_e32 v24, v29
	v_mov_b32_e32 v28, v30
	v_mov_b32_e32 v29, v26
	v_mov_b32_e32 v26, v31
	v_mov_b32_e32 v30, v16
	v_mov_b32_e32 v31, v20
	v_mov_b32_e32 v20, v17
	v_add_u32_e32 v220, 0xb0, v154
	v_ashrrev_i32_e32 v221, 31, v220
	v_lshlrev_b64 v[220:221], 6, v[220:221]
	v_lshl_add_u64 v[220:221], s[74:75], 0, v[220:221]
	global_load_dwordx4 v[204:207], v[220:221], off
	global_load_dwordx4 v[208:211], v[220:221], off offset:16
	global_load_dwordx4 v[212:215], v[220:221], off offset:32
	global_load_dwordx4 v[216:219], v[220:221], off offset:48
	global_store_dwordx4 v[234:235], v[228:231], off
	s_waitcnt vmcnt(7)
	v_pk_add_f32 v[188:189], v[188:189], v[190:191]
	v_pk_add_f32 v[192:193], v[192:193], v[194:195]
	s_waitcnt vmcnt(5)
	v_pk_add_f32 v[196:197], v[196:197], v[198:199]
	v_pk_add_f32 v[200:201], v[200:201], v[202:203]
	v_pk_add_f32 v[188:189], v[188:189], v[192:193]
	v_pk_add_f32 v[196:197], v[196:197], v[200:201]
	v_mul_f32_e32 v50, v50, v51
	v_mul_f32_e32 v24, v24, v25
	v_mul_f32_e32 v28, v28, v29
	v_mul_f32_e32 v20, v20, v21
	v_pk_add_f32 v[188:189], v[188:189], v[196:197]
	v_mul_f32_e32 v18, v18, v22
	v_mul_f32_e32 v26, v26, v27
	v_mul_f32_e32 v30, v30, v31
	v_mul_f32_e32 v19, v19, v23
	v_add_f32_e32 v188, v188, v189
	v_fmamk_f32 v188, v188, 0x3a800000, v163
	v_rsq_f32_e32 v189, v188
	s_nop 0
	v_mul_f32_e32 v189, 0xbfb8aa3b, v189
	v_mul_f32_e32 v51, v189, v51
	v_mul_f32_e32 v25, v189, v25
	v_mul_f32_e32 v29, v189, v29
	v_mul_f32_e32 v21, v189, v21
	v_mul_f32_e32 v22, v189, v22
	v_mul_f32_e32 v27, v189, v27
	v_mul_f32_e32 v31, v189, v31
	v_mul_f32_e32 v23, v189, v23
	v_exp_f32_e32 v51, v51
	v_exp_f32_e32 v25, v25
	v_exp_f32_e32 v29, v29
	v_exp_f32_e32 v21, v21
	v_exp_f32_e32 v22, v22
	v_exp_f32_e32 v27, v27
	v_exp_f32_e32 v31, v31
	v_exp_f32_e32 v23, v23
	v_fma_f32 v51, v51, v188, v188
	v_fma_f32 v25, v25, v188, v188
	v_fma_f32 v29, v29, v188, v188
	v_fma_f32 v21, v21, v188, v188
	v_fma_f32 v22, v22, v188, v188
	v_fma_f32 v27, v27, v188, v188
	v_fma_f32 v31, v31, v188, v188
	v_fma_f32 v23, v23, v188, v188
	v_rcp_f32_e32 v51, v51
	v_rcp_f32_e32 v25, v25
	v_rcp_f32_e32 v29, v29
	v_rcp_f32_e32 v21, v21
	v_rcp_f32_e32 v22, v22
	v_rcp_f32_e32 v27, v27
	v_rcp_f32_e32 v31, v31
	v_rcp_f32_e32 v23, v23
	v_mul_f32_e32 v50, v50, v51
	v_mul_f32_e32 v24, v24, v25
	v_mul_f32_e32 v28, v28, v29
	v_mul_f32_e32 v20, v20, v21
	v_mul_f32_e32 v18, v18, v22
	v_mul_f32_e32 v26, v26, v27
	v_mul_f32_e32 v30, v30, v31
	v_mul_f32_e32 v19, v19, v23
	v_cvt_pk_bf16_f32 v224, v50, v24
	v_cvt_pk_bf16_f32 v225, v28, v26
	v_cvt_pk_bf16_f32 v226, v30, v20
	v_cvt_pk_bf16_f32 v227, v18, v19
	v_mad_i64_i32 v[20:21], s[30:31], v48, s54, v[120:121]
	v_lshl_add_u64 v[20:21], v[20:21], 0, s[28:29]
	v_lshl_add_u64 v[20:21], v[20:21], 0, s[8:9]
	v_add_u32_e32 v32, 0xb0, v154
	v_lshl_add_u64 v[20:21], v[20:21], 0, v[136:137]
	v_ashrrev_i32_e32 v33, 31, v32
	v_mov_b32_e32 v232, v20
	v_mov_b32_e32 v233, v21
	v_mov_b32_e32 v34, v12
	v_mov_b32_e32 v35, v8
	v_lshlrev_b64 v[16:17], 6, v[32:33]
	v_lshl_add_u64 v[28:29], s[74:75], 0, v[16:17]
	s_nop 0
	v_mov_b32_e32 v8, v13
	v_mov_b32_e32 v12, v14
	v_mov_b32_e32 v13, v10
	v_mov_b32_e32 v10, v15
	v_mov_b32_e32 v14, v0
	v_mov_b32_e32 v15, v4
	v_mov_b32_e32 v4, v1
	global_store_dwordx4 v[232:233], v[224:227], off
	s_waitcnt vmcnt(3)
	v_pk_add_f32 v[204:205], v[204:205], v[206:207]
	v_pk_add_f32 v[208:209], v[208:209], v[210:211]
	s_waitcnt vmcnt(1)
	v_pk_add_f32 v[212:213], v[212:213], v[214:215]
	v_pk_add_f32 v[216:217], v[216:217], v[218:219]
	v_pk_add_f32 v[204:205], v[204:205], v[208:209]
	v_pk_add_f32 v[212:213], v[212:213], v[216:217]
	v_mul_f32_e32 v34, v34, v35
	v_mul_f32_e32 v8, v8, v9
	v_mul_f32_e32 v12, v12, v13
	v_mul_f32_e32 v4, v4, v5
	v_pk_add_f32 v[204:205], v[204:205], v[212:213]
	v_mul_f32_e32 v2, v2, v6
	v_mul_f32_e32 v10, v10, v11
	v_mul_f32_e32 v14, v14, v15
	v_mul_f32_e32 v3, v3, v7
	v_add_f32_e32 v204, v204, v205
	v_fmamk_f32 v204, v204, 0x3a800000, v163
	v_rsq_f32_e32 v205, v204
	s_nop 0
	v_mul_f32_e32 v205, 0xbfb8aa3b, v205
	v_mul_f32_e32 v35, v205, v35
	v_mul_f32_e32 v9, v205, v9
	v_mul_f32_e32 v13, v205, v13
	v_mul_f32_e32 v5, v205, v5
	v_mul_f32_e32 v6, v205, v6
	v_mul_f32_e32 v11, v205, v11
	v_mul_f32_e32 v15, v205, v15
	v_mul_f32_e32 v7, v205, v7
	v_exp_f32_e32 v35, v35
	v_exp_f32_e32 v9, v9
	v_exp_f32_e32 v13, v13
	v_exp_f32_e32 v5, v5
	v_exp_f32_e32 v6, v6
	v_exp_f32_e32 v11, v11
	v_exp_f32_e32 v15, v15
	v_exp_f32_e32 v7, v7
	v_fma_f32 v35, v35, v204, v204
	v_fma_f32 v9, v9, v204, v204
	v_fma_f32 v13, v13, v204, v204
	v_fma_f32 v5, v5, v204, v204
	v_fma_f32 v6, v6, v204, v204
	v_fma_f32 v11, v11, v204, v204
	v_fma_f32 v15, v15, v204, v204
	v_fma_f32 v7, v7, v204, v204
	v_rcp_f32_e32 v35, v35
	v_rcp_f32_e32 v9, v9
	v_rcp_f32_e32 v13, v13
	v_rcp_f32_e32 v5, v5
	v_rcp_f32_e32 v6, v6
	v_rcp_f32_e32 v11, v11
	v_rcp_f32_e32 v15, v15
	v_rcp_f32_e32 v7, v7
	v_mul_f32_e32 v34, v34, v35
	v_mul_f32_e32 v8, v8, v9
	v_mul_f32_e32 v12, v12, v13
	v_mul_f32_e32 v4, v4, v5
	v_mul_f32_e32 v2, v2, v6
	v_mul_f32_e32 v10, v10, v11
	v_mul_f32_e32 v14, v14, v15
	v_mul_f32_e32 v3, v3, v7
	v_cvt_pk_bf16_f32 v228, v34, v8
	v_cvt_pk_bf16_f32 v229, v12, v10
	v_cvt_pk_bf16_f32 v230, v14, v4
	v_cvt_pk_bf16_f32 v231, v2, v3
	v_mad_i64_i32 v[4:5], s[30:31], v32, s54, v[120:121]
	v_lshl_add_u64 v[4:5], v[4:5], 0, s[28:29]
	v_lshl_add_u64 v[4:5], v[4:5], 0, s[8:9]
	v_lshl_add_u64 v[4:5], v[4:5], 0, v[136:137]
	global_store_dwordx4 v[4:5], v[228:231], off
	s_nop 1
	s_andn2_b64 vcc, exec, s[4:5]
	s_mov_b64 s[4:5], -1
	s_cbranch_vccnz .LBB0_1127
	s_branch .LBB0_1161
